# retention: K LDS-DMAs issued right after the barrier (no LDS reads in flight), V LDS-DMAs in the VALU-only tail of the region
# speedup vs baseline: 1.0396x; 1.0015x over previous
; #define RET_BAR() do { asm volatile("s_waitcnt lgkmcnt(0)" ::: "memory"); __builtin_amdgcn_s_barrier(); asm volatile("" ::: "memory"); } while (0)
; #define RET_LOADV(t) do { RET_KV(t) const char* vb_ = kb_ + (1024 + h * 256) * 2; const unsigned lo_ = (unsigned)(tid >> 6) * kp_ + (unsigned)(tid & 63) * 16u; \
;         _Pragma("unroll") for (int i_ = 0; i_ < 8; ++i_) vr[i_] = *(const u32x4*)(vb_ + (size_t)(8u * i_) * kp_ + lo_); } while (0)
; #define RET_STOREV() do { _Pragma("unroll") for (int i_ = 0; i_ < 8; ++i_) *(LAS u32x4*)(Vs + ((tid >> 6) + 8 * i_) * 1040 + (tid & 63) * 16) = vr[i_]; } while (0)
; __device__ __forceinline__ void ret_unit(ldsp lds, bf16_t* R, const bf16_t* RC, int b, int h, int qblk, float lgf2, float lgb2, const int tid_in) {
;     ...
;     for (int t = 0; t < 36; ++t) {
;         int tl_ = tid_outer; asm volatile("" : "+v"(tl_));
;         const int tid = tl_, lane = tid & 63, l15 = lane & 15, lg = lane >> 4;
;         if (wid < 4) { RET_PV(t); if (t + 1 < 36) RET_S(t + 1, TI(t + 1)); }
;         else { if (t + 1 < 36) RET_S(t + 1, TI(t + 1)); RET_PV(t); }
;         RET_BAR();
;         asm volatile("s_waitcnt vmcnt(0)" ::: "memory");
;         if (t + 1 < 36) RET_STOREV();
;         if (t + 2 < 36) RET_LOADV(TI(t + 2));
;         if (t + 3 < 36) RET_DMAK(TI(t + 3), (t + 1) & 1);
;         RET_BAR();
.Lret_loop:
	s_add_i32 s41, s27, 1
	v_readlane_b32 s42, v240, s41
	v_readlane_b32 s43, v241, s41
	v_readlane_b32 s4, v237, s41
	s_mov_b32 s5, s4
	s_nop 0
	v_cndmask_b32_e64 v230, v191, v189, s[4:5]
	v_cndmask_b32_e64 v231, v192, v190, s[4:5]
	v_cndmask_b32_e64 v232, v198, v193, s[4:5]
	v_cndmask_b32_e64 v233, v199, v194, s[4:5]
	v_cndmask_b32_e64 v234, v200, v195, s[4:5]
	v_cndmask_b32_e64 v235, v202, v197, s[4:5]
	s_add_i32 m0, s54, 0
	s_nop 0
	global_load_lds_dwordx4 v230, s[42:43]
	s_add_i32 m0, s54, 1024
	s_nop 0
	global_load_lds_dwordx4 v231, s[42:43]
	s_cmp_eq_u32 s38, 0
	s_cbranch_scc0 .Lret_regY_7
	ds_read_b128 v[102:105], v182 offset:16384
	ds_read_b128 v[106:109], v246 offset:16384
	ds_read_b128 v[110:113], v247 offset:16384
	ds_read_b128 v[114:117], v248 offset:16384
	ds_read_b128 v[118:121], v182 offset:16640
	ds_read_b128 v[122:125], v246 offset:16640
	ds_read_b128 v[126:129], v247 offset:16640
	ds_read_b128 v[130:133], v248 offset:16640
	ds_read_b128 v[134:137], v187 offset:0
	ds_read_b128 v[138:141], v187 offset:1280
	ds_read_b128 v[142:145], v187 offset:2560
	ds_read_b128 v[146:149], v187 offset:3840
	s_waitcnt lgkmcnt(11)
	v_mfma_f32_16x16x32_bf16 v[98:101], v[102:105], v[64:67], 0
	s_waitcnt lgkmcnt(10)
	v_mfma_f32_16x16x32_bf16 v[98:101], v[106:109], v[68:71], v[98:101]
	s_waitcnt lgkmcnt(9)
	v_mfma_f32_16x16x32_bf16 v[98:101], v[110:113], v[72:75], v[98:101]
	s_waitcnt lgkmcnt(8)
	v_mfma_f32_16x16x32_bf16 v[98:101], v[114:117], v[76:79], v[98:101]
	s_waitcnt lgkmcnt(7)
	v_mfma_f32_16x16x32_bf16 v[98:101], v[118:121], v[80:83], v[98:101]
	s_waitcnt lgkmcnt(6)
	v_mfma_f32_16x16x32_bf16 v[98:101], v[122:125], v[84:87], v[98:101]
	s_waitcnt lgkmcnt(5)
	v_mfma_f32_16x16x32_bf16 v[98:101], v[126:129], v[88:91], v[98:101]
	s_waitcnt lgkmcnt(4)
	v_mfma_f32_16x16x32_bf16 v[98:101], v[130:133], v[92:95], v[98:101]
	s_waitcnt lgkmcnt(0)
	v_mfma_f32_16x16x32_bf16 v[0:3], v[150:153], v[134:137], v[0:3]
	v_mfma_f32_16x16x32_bf16 v[16:19], v[154:157], v[134:137], v[16:19]
	v_mfma_f32_16x16x32_bf16 v[32:35], v[158:161], v[134:137], v[32:35]
	v_mfma_f32_16x16x32_bf16 v[48:51], v[162:165], v[134:137], v[48:51]
	v_mfma_f32_16x16x32_bf16 v[4:7], v[150:153], v[138:141], v[4:7]
	v_mfma_f32_16x16x32_bf16 v[20:23], v[154:157], v[138:141], v[20:23]
	v_mfma_f32_16x16x32_bf16 v[36:39], v[158:161], v[138:141], v[36:39]
	v_mfma_f32_16x16x32_bf16 v[52:55], v[162:165], v[138:141], v[52:55]
	v_mfma_f32_16x16x32_bf16 v[8:11], v[150:153], v[142:145], v[8:11]
	v_mfma_f32_16x16x32_bf16 v[24:27], v[154:157], v[142:145], v[24:27]
	v_mfma_f32_16x16x32_bf16 v[40:43], v[158:161], v[142:145], v[40:43]
	v_mfma_f32_16x16x32_bf16 v[56:59], v[162:165], v[142:145], v[56:59]
	v_mfma_f32_16x16x32_bf16 v[12:15], v[150:153], v[146:149], v[12:15]
	v_mfma_f32_16x16x32_bf16 v[28:31], v[154:157], v[146:149], v[28:31]
	v_mfma_f32_16x16x32_bf16 v[44:47], v[158:161], v[146:149], v[44:47]
	v_mfma_f32_16x16x32_bf16 v[60:63], v[162:165], v[146:149], v[60:63]
	v_mul_f32_e32 v170, v98, v242
	v_mul_f32_e32 v171, v99, v243
	v_mul_f32_e32 v172, v100, v244
	v_mul_f32_e32 v173, v101, v245
	v_cvt_pk_bf16_f32 v174, v170, v171
	v_cvt_pk_bf16_f32 v175, v172, v173
	ds_write_b64 v188, v[174:175] offset:5120
	s_waitcnt vmcnt(6)
	s_add_i32 m0, s55, 0
	s_nop 0
	global_load_lds_dwordx4 v232, s[42:43]
	s_add_i32 m0, s55, 1024
	s_nop 0
	global_load_lds_dwordx4 v233, s[42:43]
	s_add_i32 m0, s55, 2048
	s_nop 0
	global_load_lds_dwordx4 v234, s[42:43]
	s_add_i32 m0, s55, 3072
	s_nop 0
	global_load_lds_dwordx4 v235, s[42:43]
	ds_read_b64_tr_b16 v[150:151], v183 offset:4096
	ds_read_b64_tr_b16 v[152:153], v183 offset:4608
	ds_read_b64_tr_b16 v[154:155], v184 offset:4096
	ds_read_b64_tr_b16 v[156:157], v184 offset:4608
	ds_read_b64_tr_b16 v[158:159], v185 offset:4096
	ds_read_b64_tr_b16 v[160:161], v185 offset:4608
	ds_read_b64_tr_b16 v[162:163], v186 offset:4096
	ds_read_b64_tr_b16 v[164:165], v186 offset:4608
	s_add_i32 s41, s27, 1
	v_readlane_b32 s37, v236, s41
	s_cmp_lt_u32 s37, 32
	s_cbranch_scc0 .Lret_wctx_9
	s_lshl_b32 s100, s37, 6
	s_cmp_eq_u32 s37, s9
	s_cbranch_scc1 .Lret_wdiag_10
	s_cmp_lt_u32 s37, s9
	s_cselect_b32 s101, s11, s12
	v_subrev_u32_e32 v170, s100, v203
	v_subrev_u32_e32 v171, s100, v204
	v_subrev_u32_e32 v172, s100, v205
	v_subrev_u32_e32 v173, s100, v206
	v_cvt_f32_i32_e32 v174, v170
	v_cvt_f32_i32_e32 v175, v171
	v_cvt_f32_i32_e32 v176, v172
	v_cvt_f32_i32_e32 v177, v173
	v_mul_f32_e64 v178, s101, |v174|
	v_mul_f32_e64 v179, s101, |v175|
	v_mul_f32_e64 v180, s101, |v176|
	v_mul_f32_e64 v181, s101, |v177|
	v_exp_f32_e32 v166, v178
	v_exp_f32_e32 v167, v179
	v_exp_f32_e32 v168, v180
	v_exp_f32_e32 v169, v181
	s_branch .Lret_wdone_11

; __device__ __forceinline__ void ret_unit(ldsp lds, bf16_t* R, const bf16_t* RC, int b, int h, int qblk, float lgf2, float lgb2, const int tid_in) {
;     ...
;         else { if (t + 1 < 36) RET_S(t + 1, TI(t + 1)); RET_PV(t); }
.Lret_regY_7:
	ds_read_b128 v[134:137], v187 offset:0
	ds_read_b128 v[138:141], v187 offset:1280
	ds_read_b128 v[142:145], v187 offset:2560
	ds_read_b128 v[146:149], v187 offset:3840
	ds_read_b128 v[102:105], v182 offset:16384
	ds_read_b128 v[106:109], v246 offset:16384
	ds_read_b128 v[110:113], v247 offset:16384
	ds_read_b128 v[114:117], v248 offset:16384
	ds_read_b128 v[118:121], v182 offset:16640
	ds_read_b128 v[122:125], v246 offset:16640
	ds_read_b128 v[126:129], v247 offset:16640
	ds_read_b128 v[130:133], v248 offset:16640
	s_waitcnt lgkmcnt(8)
	v_mfma_f32_16x16x32_bf16 v[0:3], v[150:153], v[134:137], v[0:3]
	v_mfma_f32_16x16x32_bf16 v[16:19], v[154:157], v[134:137], v[16:19]
	v_mfma_f32_16x16x32_bf16 v[32:35], v[158:161], v[134:137], v[32:35]
	v_mfma_f32_16x16x32_bf16 v[48:51], v[162:165], v[134:137], v[48:51]
	v_mfma_f32_16x16x32_bf16 v[4:7], v[150:153], v[138:141], v[4:7]
	v_mfma_f32_16x16x32_bf16 v[20:23], v[154:157], v[138:141], v[20:23]
	v_mfma_f32_16x16x32_bf16 v[36:39], v[158:161], v[138:141], v[36:39]
	v_mfma_f32_16x16x32_bf16 v[52:55], v[162:165], v[138:141], v[52:55]
	v_mfma_f32_16x16x32_bf16 v[8:11], v[150:153], v[142:145], v[8:11]
	v_mfma_f32_16x16x32_bf16 v[24:27], v[154:157], v[142:145], v[24:27]
	v_mfma_f32_16x16x32_bf16 v[40:43], v[158:161], v[142:145], v[40:43]
	v_mfma_f32_16x16x32_bf16 v[56:59], v[162:165], v[142:145], v[56:59]
	v_mfma_f32_16x16x32_bf16 v[12:15], v[150:153], v[146:149], v[12:15]
	v_mfma_f32_16x16x32_bf16 v[28:31], v[154:157], v[146:149], v[28:31]
	v_mfma_f32_16x16x32_bf16 v[44:47], v[158:161], v[146:149], v[44:47]
	v_mfma_f32_16x16x32_bf16 v[60:63], v[162:165], v[146:149], v[60:63]
	s_waitcnt lgkmcnt(7)
	v_mfma_f32_16x16x32_bf16 v[98:101], v[102:105], v[64:67], 0
	s_waitcnt lgkmcnt(6)
	v_mfma_f32_16x16x32_bf16 v[98:101], v[106:109], v[68:71], v[98:101]
	s_waitcnt lgkmcnt(5)
	v_mfma_f32_16x16x32_bf16 v[98:101], v[110:113], v[72:75], v[98:101]
	s_waitcnt lgkmcnt(4)
	v_mfma_f32_16x16x32_bf16 v[98:101], v[114:117], v[76:79], v[98:101]
	s_waitcnt lgkmcnt(3)
	v_mfma_f32_16x16x32_bf16 v[98:101], v[118:121], v[80:83], v[98:101]
	s_waitcnt lgkmcnt(2)
	v_mfma_f32_16x16x32_bf16 v[98:101], v[122:125], v[84:87], v[98:101]
	s_waitcnt lgkmcnt(1)
	v_mfma_f32_16x16x32_bf16 v[98:101], v[126:129], v[88:91], v[98:101]
	s_waitcnt lgkmcnt(0)
	v_mfma_f32_16x16x32_bf16 v[98:101], v[130:133], v[92:95], v[98:101]
	s_add_i32 s41, s27, 1
	v_readlane_b32 s37, v236, s41
	s_cmp_lt_u32 s37, 32
	s_cbranch_scc0 .Lret_wctx_12
	s_lshl_b32 s100, s37, 6
	s_cmp_eq_u32 s37, s9
	s_cbranch_scc1 .Lret_wdiag_13
	s_cmp_lt_u32 s37, s9
	s_cselect_b32 s101, s11, s12
	v_subrev_u32_e32 v170, s100, v203
	v_subrev_u32_e32 v171, s100, v204
	v_subrev_u32_e32 v172, s100, v205
	v_subrev_u32_e32 v173, s100, v206
	v_cvt_f32_i32_e32 v174, v170
	v_cvt_f32_i32_e32 v175, v171
	v_cvt_f32_i32_e32 v176, v172
	v_cvt_f32_i32_e32 v177, v173
	v_mul_f32_e64 v178, s101, |v174|
	v_mul_f32_e64 v179, s101, |v175|
	v_mul_f32_e64 v180, s101, |v176|
	v_mul_f32_e64 v181, s101, |v177|
	v_exp_f32_e32 v166, v178
	v_exp_f32_e32 v167, v179
	v_exp_f32_e32 v168, v180
	v_exp_f32_e32 v169, v181
	s_branch .Lret_wdone_14

; #define RET_BAR() do { asm volatile("s_waitcnt lgkmcnt(0)" ::: "memory"); __builtin_amdgcn_s_barrier(); asm volatile("" ::: "memory"); } while (0)
; #define RET_LOADV(t) do { RET_KV(t) const char* vb_ = kb_ + (1024 + h * 256) * 2; const unsigned lo_ = (unsigned)(tid >> 6) * kp_ + (unsigned)(tid & 63) * 16u; \
;         _Pragma("unroll") for (int i_ = 0; i_ < 8; ++i_) vr[i_] = *(const u32x4*)(vb_ + (size_t)(8u * i_) * kp_ + lo_); } while (0)
; #define RET_STOREV() do { _Pragma("unroll") for (int i_ = 0; i_ < 8; ++i_) *(LAS u32x4*)(Vs + ((tid >> 6) + 8 * i_) * 1040 + (tid & 63) * 16) = vr[i_]; } while (0)
; __device__ __forceinline__ void ret_unit(ldsp lds, bf16_t* R, const bf16_t* RC, int b, int h, int qblk, float lgf2, float lgb2, const int tid_in) {
;     ...
;     for (int t = 0; t < 36; ++t) {
;         int tl_ = tid_outer; asm volatile("" : "+v"(tl_));
;         const int tid = tl_, lane = tid & 63, l15 = lane & 15, lg = lane >> 4;
;         if (wid < 4) { RET_PV(t); if (t + 1 < 36) RET_S(t + 1, TI(t + 1)); }
;         else { if (t + 1 < 36) RET_S(t + 1, TI(t + 1)); RET_PV(t); }
;         RET_BAR();
;         asm volatile("s_waitcnt vmcnt(0)" ::: "memory");
;         if (t + 1 < 36) RET_STOREV();
;         if (t + 2 < 36) RET_LOADV(TI(t + 2));
;         if (t + 3 < 36) RET_DMAK(TI(t + 3), (t + 1) & 1);
;         RET_BAR();
.Lret_wdone_14:
	v_mul_f32_e32 v170, v98, v242
	v_mul_f32_e32 v171, v99, v243
	v_mul_f32_e32 v172, v100, v244
	v_mul_f32_e32 v173, v101, v245
	v_cvt_pk_bf16_f32 v174, v170, v171
	v_cvt_pk_bf16_f32 v175, v172, v173
	ds_write_b64 v188, v[174:175] offset:5120
	s_waitcnt vmcnt(6)
	s_add_i32 m0, s55, 0
	s_nop 0
	global_load_lds_dwordx4 v232, s[42:43]
	s_add_i32 m0, s55, 1024
	s_nop 0
	global_load_lds_dwordx4 v233, s[42:43]
	s_add_i32 m0, s55, 2048
	s_nop 0
	global_load_lds_dwordx4 v234, s[42:43]
	s_add_i32 m0, s55, 3072
	s_nop 0
	global_load_lds_dwordx4 v235, s[42:43]
	ds_read_b64_tr_b16 v[150:151], v183 offset:4096
	ds_read_b64_tr_b16 v[152:153], v183 offset:4608
	ds_read_b64_tr_b16 v[154:155], v184 offset:4096
	ds_read_b64_tr_b16 v[156:157], v184 offset:4608
	ds_read_b64_tr_b16 v[158:159], v185 offset:4096
	ds_read_b64_tr_b16 v[160:161], v185 offset:4608
	ds_read_b64_tr_b16 v[162:163], v186 offset:4096
	ds_read_b64_tr_b16 v[164:165], v186 offset:4608
	s_waitcnt lgkmcnt(8)
.Lret_regJ_8:
	s_barrier
	s_add_i32 s41, s27, 2
	v_readlane_b32 s42, v238, s41
	v_readlane_b32 s43, v239, s41
	v_readlane_b32 s4, v237, s41
	s_mov_b32 s5, s4
	s_nop 0
	v_cndmask_b32_e64 v230, v191, v189, s[4:5]
	v_cndmask_b32_e64 v231, v192, v190, s[4:5]
	v_cndmask_b32_e64 v232, v198, v193, s[4:5]
	v_cndmask_b32_e64 v233, v199, v194, s[4:5]
	v_cndmask_b32_e64 v234, v200, v195, s[4:5]
	v_cndmask_b32_e64 v235, v202, v197, s[4:5]
	s_add_i32 m0, s54, 16384
	s_nop 0
	global_load_lds_dwordx4 v230, s[42:43]
	s_add_i32 m0, s54, 17408
	s_nop 0
	global_load_lds_dwordx4 v231, s[42:43]
	s_cmp_eq_u32 s38, 0
	s_cbranch_scc0 .Lret_regY_15
	ds_read_b128 v[102:105], v182 offset:32768
	ds_read_b128 v[106:109], v246 offset:32768
	ds_read_b128 v[110:113], v247 offset:32768
	ds_read_b128 v[114:117], v248 offset:32768
	ds_read_b128 v[118:121], v182 offset:33024
	ds_read_b128 v[122:125], v246 offset:33024
	ds_read_b128 v[126:129], v247 offset:33024
	ds_read_b128 v[130:133], v248 offset:33024
	ds_read_b128 v[134:137], v187 offset:5120
	ds_read_b128 v[138:141], v187 offset:6400
	ds_read_b128 v[142:145], v187 offset:7680
	ds_read_b128 v[146:149], v187 offset:8960
	s_waitcnt lgkmcnt(11)
	v_mfma_f32_16x16x32_bf16 v[98:101], v[102:105], v[64:67], 0
	s_waitcnt lgkmcnt(10)
	v_mfma_f32_16x16x32_bf16 v[98:101], v[106:109], v[68:71], v[98:101]
	s_waitcnt lgkmcnt(9)
	v_mfma_f32_16x16x32_bf16 v[98:101], v[110:113], v[72:75], v[98:101]
	s_waitcnt lgkmcnt(8)
	v_mfma_f32_16x16x32_bf16 v[98:101], v[114:117], v[76:79], v[98:101]
	s_waitcnt lgkmcnt(7)
	v_mfma_f32_16x16x32_bf16 v[98:101], v[118:121], v[80:83], v[98:101]
	s_waitcnt lgkmcnt(6)
	v_mfma_f32_16x16x32_bf16 v[98:101], v[122:125], v[84:87], v[98:101]
	s_waitcnt lgkmcnt(5)
	v_mfma_f32_16x16x32_bf16 v[98:101], v[126:129], v[88:91], v[98:101]
	s_waitcnt lgkmcnt(4)
	v_mfma_f32_16x16x32_bf16 v[98:101], v[130:133], v[92:95], v[98:101]
	s_waitcnt lgkmcnt(0)
	v_mfma_f32_16x16x32_bf16 v[0:3], v[150:153], v[134:137], v[0:3]
	v_mfma_f32_16x16x32_bf16 v[16:19], v[154:157], v[134:137], v[16:19]
	v_mfma_f32_16x16x32_bf16 v[32:35], v[158:161], v[134:137], v[32:35]
	v_mfma_f32_16x16x32_bf16 v[48:51], v[162:165], v[134:137], v[48:51]
	v_mfma_f32_16x16x32_bf16 v[4:7], v[150:153], v[138:141], v[4:7]
	v_mfma_f32_16x16x32_bf16 v[20:23], v[154:157], v[138:141], v[20:23]
	v_mfma_f32_16x16x32_bf16 v[36:39], v[158:161], v[138:141], v[36:39]
	v_mfma_f32_16x16x32_bf16 v[52:55], v[162:165], v[138:141], v[52:55]
	v_mfma_f32_16x16x32_bf16 v[8:11], v[150:153], v[142:145], v[8:11]
	v_mfma_f32_16x16x32_bf16 v[24:27], v[154:157], v[142:145], v[24:27]
	v_mfma_f32_16x16x32_bf16 v[40:43], v[158:161], v[142:145], v[40:43]
	v_mfma_f32_16x16x32_bf16 v[56:59], v[162:165], v[142:145], v[56:59]
	v_mfma_f32_16x16x32_bf16 v[12:15], v[150:153], v[146:149], v[12:15]
	v_mfma_f32_16x16x32_bf16 v[28:31], v[154:157], v[146:149], v[28:31]
	v_mfma_f32_16x16x32_bf16 v[44:47], v[158:161], v[146:149], v[44:47]
	v_mfma_f32_16x16x32_bf16 v[60:63], v[162:165], v[146:149], v[60:63]
	v_mul_f32_e32 v170, v98, v166
	v_mul_f32_e32 v171, v99, v167
	v_mul_f32_e32 v172, v100, v168
	v_mul_f32_e32 v173, v101, v169
	v_cvt_pk_bf16_f32 v174, v170, v171
	v_cvt_pk_bf16_f32 v175, v172, v173
	ds_write_b64 v188, v[174:175] offset:0
	s_waitcnt vmcnt(6)
	s_add_i32 m0, s55, 4096
	s_nop 0
	global_load_lds_dwordx4 v232, s[42:43]
	s_add_i32 m0, s55, 5120
	s_nop 0
	global_load_lds_dwordx4 v233, s[42:43]
	s_add_i32 m0, s55, 6144
	s_nop 0
	global_load_lds_dwordx4 v234, s[42:43]
	s_add_i32 m0, s55, 7168
	s_nop 0
	global_load_lds_dwordx4 v235, s[42:43]
	ds_read_b64_tr_b16 v[150:151], v183 offset:8192
	ds_read_b64_tr_b16 v[152:153], v183 offset:8704
	ds_read_b64_tr_b16 v[154:155], v184 offset:8192
	ds_read_b64_tr_b16 v[156:157], v184 offset:8704
	ds_read_b64_tr_b16 v[158:159], v185 offset:8192
	ds_read_b64_tr_b16 v[160:161], v185 offset:8704
	ds_read_b64_tr_b16 v[162:163], v186 offset:8192
	ds_read_b64_tr_b16 v[164:165], v186 offset:8704
	s_add_i32 s41, s27, 1
	v_readlane_b32 s37, v236, s41
	s_cmp_lt_u32 s37, 32
	s_cbranch_scc0 .Lret_wctx_17
	s_lshl_b32 s100, s37, 6
	s_add_i32 s100, s100, 32
	s_cmp_eq_u32 s37, s9
	s_cbranch_scc1 .Lret_wdiag_18
	s_cmp_lt_u32 s37, s9
	s_cselect_b32 s101, s11, s12
	v_subrev_u32_e32 v170, s100, v203
	v_subrev_u32_e32 v171, s100, v204
	v_subrev_u32_e32 v172, s100, v205
	v_subrev_u32_e32 v173, s100, v206
	v_cvt_f32_i32_e32 v174, v170
	v_cvt_f32_i32_e32 v175, v171
	v_cvt_f32_i32_e32 v176, v172
	v_cvt_f32_i32_e32 v177, v173
	v_mul_f32_e64 v178, s101, |v174|
	v_mul_f32_e64 v179, s101, |v175|
	v_mul_f32_e64 v180, s101, |v176|
	v_mul_f32_e64 v181, s101, |v177|
	v_exp_f32_e32 v242, v178
	v_exp_f32_e32 v243, v179
	v_exp_f32_e32 v244, v180
	v_exp_f32_e32 v245, v181
	s_branch .Lret_wdone_19

; __device__ __forceinline__ void ret_unit(ldsp lds, bf16_t* R, const bf16_t* RC, int b, int h, int qblk, float lgf2, float lgb2, const int tid_in) {
;     ...
;         else { if (t + 1 < 36) RET_S(t + 1, TI(t + 1)); RET_PV(t); }
.Lret_regY_15:
	ds_read_b128 v[134:137], v187 offset:5120
	ds_read_b128 v[138:141], v187 offset:6400
	ds_read_b128 v[142:145], v187 offset:7680
	ds_read_b128 v[146:149], v187 offset:8960
	ds_read_b128 v[102:105], v182 offset:32768
	ds_read_b128 v[106:109], v246 offset:32768
	ds_read_b128 v[110:113], v247 offset:32768
	ds_read_b128 v[114:117], v248 offset:32768
	ds_read_b128 v[118:121], v182 offset:33024
	ds_read_b128 v[122:125], v246 offset:33024
	ds_read_b128 v[126:129], v247 offset:33024
	ds_read_b128 v[130:133], v248 offset:33024
	s_waitcnt lgkmcnt(8)
	v_mfma_f32_16x16x32_bf16 v[0:3], v[150:153], v[134:137], v[0:3]
	v_mfma_f32_16x16x32_bf16 v[16:19], v[154:157], v[134:137], v[16:19]
	v_mfma_f32_16x16x32_bf16 v[32:35], v[158:161], v[134:137], v[32:35]
	v_mfma_f32_16x16x32_bf16 v[48:51], v[162:165], v[134:137], v[48:51]
	v_mfma_f32_16x16x32_bf16 v[4:7], v[150:153], v[138:141], v[4:7]
	v_mfma_f32_16x16x32_bf16 v[20:23], v[154:157], v[138:141], v[20:23]
	v_mfma_f32_16x16x32_bf16 v[36:39], v[158:161], v[138:141], v[36:39]
	v_mfma_f32_16x16x32_bf16 v[52:55], v[162:165], v[138:141], v[52:55]
	v_mfma_f32_16x16x32_bf16 v[8:11], v[150:153], v[142:145], v[8:11]
	v_mfma_f32_16x16x32_bf16 v[24:27], v[154:157], v[142:145], v[24:27]
	v_mfma_f32_16x16x32_bf16 v[40:43], v[158:161], v[142:145], v[40:43]
	v_mfma_f32_16x16x32_bf16 v[56:59], v[162:165], v[142:145], v[56:59]
	v_mfma_f32_16x16x32_bf16 v[12:15], v[150:153], v[146:149], v[12:15]
	v_mfma_f32_16x16x32_bf16 v[28:31], v[154:157], v[146:149], v[28:31]
	v_mfma_f32_16x16x32_bf16 v[44:47], v[158:161], v[146:149], v[44:47]
	v_mfma_f32_16x16x32_bf16 v[60:63], v[162:165], v[146:149], v[60:63]
	s_waitcnt lgkmcnt(7)
	v_mfma_f32_16x16x32_bf16 v[98:101], v[102:105], v[64:67], 0
	s_waitcnt lgkmcnt(6)
	v_mfma_f32_16x16x32_bf16 v[98:101], v[106:109], v[68:71], v[98:101]
	s_waitcnt lgkmcnt(5)
	v_mfma_f32_16x16x32_bf16 v[98:101], v[110:113], v[72:75], v[98:101]
	s_waitcnt lgkmcnt(4)
	v_mfma_f32_16x16x32_bf16 v[98:101], v[114:117], v[76:79], v[98:101]
	s_waitcnt lgkmcnt(3)
	v_mfma_f32_16x16x32_bf16 v[98:101], v[118:121], v[80:83], v[98:101]
	s_waitcnt lgkmcnt(2)
	v_mfma_f32_16x16x32_bf16 v[98:101], v[122:125], v[84:87], v[98:101]
	s_waitcnt lgkmcnt(1)
	v_mfma_f32_16x16x32_bf16 v[98:101], v[126:129], v[88:91], v[98:101]
	s_waitcnt lgkmcnt(0)
	v_mfma_f32_16x16x32_bf16 v[98:101], v[130:133], v[92:95], v[98:101]
	s_add_i32 s41, s27, 1
	v_readlane_b32 s37, v236, s41
	s_cmp_lt_u32 s37, 32
	s_cbranch_scc0 .Lret_wctx_20
	s_lshl_b32 s100, s37, 6
	s_add_i32 s100, s100, 32
	s_cmp_eq_u32 s37, s9
	s_cbranch_scc1 .Lret_wdiag_21
	s_cmp_lt_u32 s37, s9
	s_cselect_b32 s101, s11, s12
	v_subrev_u32_e32 v170, s100, v203
	v_subrev_u32_e32 v171, s100, v204
	v_subrev_u32_e32 v172, s100, v205
	v_subrev_u32_e32 v173, s100, v206
	v_cvt_f32_i32_e32 v174, v170
	v_cvt_f32_i32_e32 v175, v171
	v_cvt_f32_i32_e32 v176, v172
	v_cvt_f32_i32_e32 v177, v173
	v_mul_f32_e64 v178, s101, |v174|
	v_mul_f32_e64 v179, s101, |v175|
	v_mul_f32_e64 v180, s101, |v176|
	v_mul_f32_e64 v181, s101, |v177|
	v_exp_f32_e32 v242, v178
	v_exp_f32_e32 v243, v179
	v_exp_f32_e32 v244, v180
	v_exp_f32_e32 v245, v181
	s_branch .Lret_wdone_22

; #define RET_BAR() do { asm volatile("s_waitcnt lgkmcnt(0)" ::: "memory"); __builtin_amdgcn_s_barrier(); asm volatile("" ::: "memory"); } while (0)
; #define RET_LOADV(t) do { RET_KV(t) const char* vb_ = kb_ + (1024 + h * 256) * 2; const unsigned lo_ = (unsigned)(tid >> 6) * kp_ + (unsigned)(tid & 63) * 16u; \
;         _Pragma("unroll") for (int i_ = 0; i_ < 8; ++i_) vr[i_] = *(const u32x4*)(vb_ + (size_t)(8u * i_) * kp_ + lo_); } while (0)
; #define RET_STOREV() do { _Pragma("unroll") for (int i_ = 0; i_ < 8; ++i_) *(LAS u32x4*)(Vs + ((tid >> 6) + 8 * i_) * 1040 + (tid & 63) * 16) = vr[i_]; } while (0)
; __device__ __forceinline__ void ret_unit(ldsp lds, bf16_t* R, const bf16_t* RC, int b, int h, int qblk, float lgf2, float lgb2, const int tid_in) {
;     ...
;     for (int t = 0; t < 36; ++t) {
;         int tl_ = tid_outer; asm volatile("" : "+v"(tl_));
;         const int tid = tl_, lane = tid & 63, l15 = lane & 15, lg = lane >> 4;
;         if (wid < 4) { RET_PV(t); if (t + 1 < 36) RET_S(t + 1, TI(t + 1)); }
;         else { if (t + 1 < 36) RET_S(t + 1, TI(t + 1)); RET_PV(t); }
;         RET_BAR();
;         asm volatile("s_waitcnt vmcnt(0)" ::: "memory");
;         if (t + 1 < 36) RET_STOREV();
;         if (t + 2 < 36) RET_LOADV(TI(t + 2));
;         if (t + 3 < 36) RET_DMAK(TI(t + 3), (t + 1) & 1);
;         RET_BAR();
.Lret_wdone_22:
	v_mul_f32_e32 v170, v98, v166
	v_mul_f32_e32 v171, v99, v167
	v_mul_f32_e32 v172, v100, v168
	v_mul_f32_e32 v173, v101, v169
	v_cvt_pk_bf16_f32 v174, v170, v171
	v_cvt_pk_bf16_f32 v175, v172, v173
	ds_write_b64 v188, v[174:175] offset:0
	s_waitcnt vmcnt(6)
	s_add_i32 m0, s55, 4096
	s_nop 0
	global_load_lds_dwordx4 v232, s[42:43]
	s_add_i32 m0, s55, 5120
	s_nop 0
	global_load_lds_dwordx4 v233, s[42:43]
	s_add_i32 m0, s55, 6144
	s_nop 0
	global_load_lds_dwordx4 v234, s[42:43]
	s_add_i32 m0, s55, 7168
	s_nop 0
	global_load_lds_dwordx4 v235, s[42:43]
	ds_read_b64_tr_b16 v[150:151], v183 offset:8192
	ds_read_b64_tr_b16 v[152:153], v183 offset:8704
	ds_read_b64_tr_b16 v[154:155], v184 offset:8192
	ds_read_b64_tr_b16 v[156:157], v184 offset:8704
	ds_read_b64_tr_b16 v[158:159], v185 offset:8192
	ds_read_b64_tr_b16 v[160:161], v185 offset:8704
	ds_read_b64_tr_b16 v[162:163], v186 offset:8192
	ds_read_b64_tr_b16 v[164:165], v186 offset:8704
	s_waitcnt lgkmcnt(8)
.Lret_regJ_16:
	s_barrier
	s_add_i32 s41, s27, 2
	v_readlane_b32 s42, v240, s41
	v_readlane_b32 s43, v241, s41
	v_readlane_b32 s4, v237, s41
	s_mov_b32 s5, s4
	s_nop 0
	v_cndmask_b32_e64 v230, v191, v189, s[4:5]
	v_cndmask_b32_e64 v231, v192, v190, s[4:5]
	v_cndmask_b32_e64 v232, v198, v193, s[4:5]
	v_cndmask_b32_e64 v233, v199, v194, s[4:5]
	v_cndmask_b32_e64 v234, v200, v195, s[4:5]
	v_cndmask_b32_e64 v235, v202, v197, s[4:5]
	s_add_i32 m0, s54, 32768
	s_nop 0
	global_load_lds_dwordx4 v230, s[42:43]
	s_add_i32 m0, s54, 33792
	s_nop 0
	global_load_lds_dwordx4 v231, s[42:43]
	s_cmp_eq_u32 s38, 0
	s_cbranch_scc0 .Lret_regY_23
	ds_read_b128 v[102:105], v182 offset:0
	ds_read_b128 v[106:109], v246 offset:0
	ds_read_b128 v[110:113], v247 offset:0
	ds_read_b128 v[114:117], v248 offset:0
	ds_read_b128 v[118:121], v182 offset:256
	ds_read_b128 v[122:125], v246 offset:256
	ds_read_b128 v[126:129], v247 offset:256
	ds_read_b128 v[130:133], v248 offset:256
	ds_read_b128 v[134:137], v187 offset:0
	ds_read_b128 v[138:141], v187 offset:1280
	ds_read_b128 v[142:145], v187 offset:2560
	ds_read_b128 v[146:149], v187 offset:3840
	s_waitcnt lgkmcnt(11)
	v_mfma_f32_16x16x32_bf16 v[98:101], v[102:105], v[64:67], 0
	s_waitcnt lgkmcnt(10)
	v_mfma_f32_16x16x32_bf16 v[98:101], v[106:109], v[68:71], v[98:101]
	s_waitcnt lgkmcnt(9)
	v_mfma_f32_16x16x32_bf16 v[98:101], v[110:113], v[72:75], v[98:101]
	s_waitcnt lgkmcnt(8)
	v_mfma_f32_16x16x32_bf16 v[98:101], v[114:117], v[76:79], v[98:101]
	s_waitcnt lgkmcnt(7)
	v_mfma_f32_16x16x32_bf16 v[98:101], v[118:121], v[80:83], v[98:101]
	s_waitcnt lgkmcnt(6)
	v_mfma_f32_16x16x32_bf16 v[98:101], v[122:125], v[84:87], v[98:101]
	s_waitcnt lgkmcnt(5)
	v_mfma_f32_16x16x32_bf16 v[98:101], v[126:129], v[88:91], v[98:101]
	s_waitcnt lgkmcnt(4)
	v_mfma_f32_16x16x32_bf16 v[98:101], v[130:133], v[92:95], v[98:101]
	s_waitcnt lgkmcnt(0)
	v_mfma_f32_16x16x32_bf16 v[0:3], v[150:153], v[134:137], v[0:3]
	v_mfma_f32_16x16x32_bf16 v[16:19], v[154:157], v[134:137], v[16:19]
	v_mfma_f32_16x16x32_bf16 v[32:35], v[158:161], v[134:137], v[32:35]
	v_mfma_f32_16x16x32_bf16 v[48:51], v[162:165], v[134:137], v[48:51]
	v_mfma_f32_16x16x32_bf16 v[4:7], v[150:153], v[138:141], v[4:7]
	v_mfma_f32_16x16x32_bf16 v[20:23], v[154:157], v[138:141], v[20:23]
	v_mfma_f32_16x16x32_bf16 v[36:39], v[158:161], v[138:141], v[36:39]
	v_mfma_f32_16x16x32_bf16 v[52:55], v[162:165], v[138:141], v[52:55]
	v_mfma_f32_16x16x32_bf16 v[8:11], v[150:153], v[142:145], v[8:11]
	v_mfma_f32_16x16x32_bf16 v[24:27], v[154:157], v[142:145], v[24:27]
	v_mfma_f32_16x16x32_bf16 v[40:43], v[158:161], v[142:145], v[40:43]
	v_mfma_f32_16x16x32_bf16 v[56:59], v[162:165], v[142:145], v[56:59]
	v_mfma_f32_16x16x32_bf16 v[12:15], v[150:153], v[146:149], v[12:15]
	v_mfma_f32_16x16x32_bf16 v[28:31], v[154:157], v[146:149], v[28:31]
	v_mfma_f32_16x16x32_bf16 v[44:47], v[158:161], v[146:149], v[44:47]
	v_mfma_f32_16x16x32_bf16 v[60:63], v[162:165], v[146:149], v[60:63]
	v_mul_f32_e32 v170, v98, v242
	v_mul_f32_e32 v171, v99, v243
	v_mul_f32_e32 v172, v100, v244
	v_mul_f32_e32 v173, v101, v245
	v_cvt_pk_bf16_f32 v174, v170, v171
	v_cvt_pk_bf16_f32 v175, v172, v173
	ds_write_b64 v188, v[174:175] offset:5120
	s_waitcnt vmcnt(6)
	s_add_i32 m0, s55, 8192
	s_nop 0
	global_load_lds_dwordx4 v232, s[42:43]
	s_add_i32 m0, s55, 9216
	s_nop 0
	global_load_lds_dwordx4 v233, s[42:43]
	s_add_i32 m0, s55, 10240
	s_nop 0
	global_load_lds_dwordx4 v234, s[42:43]
	s_add_i32 m0, s55, 11264
	s_nop 0
	global_load_lds_dwordx4 v235, s[42:43]
	ds_read_b64_tr_b16 v[150:151], v183 offset:0
	ds_read_b64_tr_b16 v[152:153], v183 offset:512
	ds_read_b64_tr_b16 v[154:155], v184 offset:0
	ds_read_b64_tr_b16 v[156:157], v184 offset:512
	ds_read_b64_tr_b16 v[158:159], v185 offset:0
	ds_read_b64_tr_b16 v[160:161], v185 offset:512
	ds_read_b64_tr_b16 v[162:163], v186 offset:0
	ds_read_b64_tr_b16 v[164:165], v186 offset:512
	s_add_i32 s41, s27, 2
	v_readlane_b32 s37, v236, s41
	s_cmp_lt_u32 s37, 32
	s_cbranch_scc0 .Lret_wctx_25
	s_lshl_b32 s100, s37, 6
	s_cmp_eq_u32 s37, s9
	s_cbranch_scc1 .Lret_wdiag_26
	s_cmp_lt_u32 s37, s9
	s_cselect_b32 s101, s11, s12
	v_subrev_u32_e32 v170, s100, v203
	v_subrev_u32_e32 v171, s100, v204
	v_subrev_u32_e32 v172, s100, v205
	v_subrev_u32_e32 v173, s100, v206
	v_cvt_f32_i32_e32 v174, v170
	v_cvt_f32_i32_e32 v175, v171
	v_cvt_f32_i32_e32 v176, v172
	v_cvt_f32_i32_e32 v177, v173
	v_mul_f32_e64 v178, s101, |v174|
	v_mul_f32_e64 v179, s101, |v175|
	v_mul_f32_e64 v180, s101, |v176|
	v_mul_f32_e64 v181, s101, |v177|
	v_exp_f32_e32 v166, v178
	v_exp_f32_e32 v167, v179
	v_exp_f32_e32 v168, v180
	v_exp_f32_e32 v169, v181
	s_branch .Lret_wdone_27

; __device__ __forceinline__ void ret_unit(ldsp lds, bf16_t* R, const bf16_t* RC, int b, int h, int qblk, float lgf2, float lgb2, const int tid_in) {
;     ...
;         else { if (t + 1 < 36) RET_S(t + 1, TI(t + 1)); RET_PV(t); }
.Lret_regY_23:
	ds_read_b128 v[134:137], v187 offset:0
	ds_read_b128 v[138:141], v187 offset:1280
	ds_read_b128 v[142:145], v187 offset:2560
	ds_read_b128 v[146:149], v187 offset:3840
	ds_read_b128 v[102:105], v182 offset:0
	ds_read_b128 v[106:109], v246 offset:0
	ds_read_b128 v[110:113], v247 offset:0
	ds_read_b128 v[114:117], v248 offset:0
	ds_read_b128 v[118:121], v182 offset:256
	ds_read_b128 v[122:125], v246 offset:256
	ds_read_b128 v[126:129], v247 offset:256
	ds_read_b128 v[130:133], v248 offset:256
	s_waitcnt lgkmcnt(8)
	v_mfma_f32_16x16x32_bf16 v[0:3], v[150:153], v[134:137], v[0:3]
	v_mfma_f32_16x16x32_bf16 v[16:19], v[154:157], v[134:137], v[16:19]
	v_mfma_f32_16x16x32_bf16 v[32:35], v[158:161], v[134:137], v[32:35]
	v_mfma_f32_16x16x32_bf16 v[48:51], v[162:165], v[134:137], v[48:51]
	v_mfma_f32_16x16x32_bf16 v[4:7], v[150:153], v[138:141], v[4:7]
	v_mfma_f32_16x16x32_bf16 v[20:23], v[154:157], v[138:141], v[20:23]
	v_mfma_f32_16x16x32_bf16 v[36:39], v[158:161], v[138:141], v[36:39]
	v_mfma_f32_16x16x32_bf16 v[52:55], v[162:165], v[138:141], v[52:55]
	v_mfma_f32_16x16x32_bf16 v[8:11], v[150:153], v[142:145], v[8:11]
	v_mfma_f32_16x16x32_bf16 v[24:27], v[154:157], v[142:145], v[24:27]
	v_mfma_f32_16x16x32_bf16 v[40:43], v[158:161], v[142:145], v[40:43]
	v_mfma_f32_16x16x32_bf16 v[56:59], v[162:165], v[142:145], v[56:59]
	v_mfma_f32_16x16x32_bf16 v[12:15], v[150:153], v[146:149], v[12:15]
	v_mfma_f32_16x16x32_bf16 v[28:31], v[154:157], v[146:149], v[28:31]
	v_mfma_f32_16x16x32_bf16 v[44:47], v[158:161], v[146:149], v[44:47]
	v_mfma_f32_16x16x32_bf16 v[60:63], v[162:165], v[146:149], v[60:63]
	s_waitcnt lgkmcnt(7)
	v_mfma_f32_16x16x32_bf16 v[98:101], v[102:105], v[64:67], 0
	s_waitcnt lgkmcnt(6)
	v_mfma_f32_16x16x32_bf16 v[98:101], v[106:109], v[68:71], v[98:101]
	s_waitcnt lgkmcnt(5)
	v_mfma_f32_16x16x32_bf16 v[98:101], v[110:113], v[72:75], v[98:101]
	s_waitcnt lgkmcnt(4)
	v_mfma_f32_16x16x32_bf16 v[98:101], v[114:117], v[76:79], v[98:101]
	s_waitcnt lgkmcnt(3)
	v_mfma_f32_16x16x32_bf16 v[98:101], v[118:121], v[80:83], v[98:101]
	s_waitcnt lgkmcnt(2)
	v_mfma_f32_16x16x32_bf16 v[98:101], v[122:125], v[84:87], v[98:101]
	s_waitcnt lgkmcnt(1)
	v_mfma_f32_16x16x32_bf16 v[98:101], v[126:129], v[88:91], v[98:101]
	s_waitcnt lgkmcnt(0)
	v_mfma_f32_16x16x32_bf16 v[98:101], v[130:133], v[92:95], v[98:101]
	s_add_i32 s41, s27, 2
	v_readlane_b32 s37, v236, s41
	s_cmp_lt_u32 s37, 32
	s_cbranch_scc0 .Lret_wctx_28
	s_lshl_b32 s100, s37, 6
	s_cmp_eq_u32 s37, s9
	s_cbranch_scc1 .Lret_wdiag_29
	s_cmp_lt_u32 s37, s9
	s_cselect_b32 s101, s11, s12
	v_subrev_u32_e32 v170, s100, v203
	v_subrev_u32_e32 v171, s100, v204
	v_subrev_u32_e32 v172, s100, v205
	v_subrev_u32_e32 v173, s100, v206
	v_cvt_f32_i32_e32 v174, v170
	v_cvt_f32_i32_e32 v175, v171
	v_cvt_f32_i32_e32 v176, v172
	v_cvt_f32_i32_e32 v177, v173
	v_mul_f32_e64 v178, s101, |v174|
	v_mul_f32_e64 v179, s101, |v175|
	v_mul_f32_e64 v180, s101, |v176|
	v_mul_f32_e64 v181, s101, |v177|
	v_exp_f32_e32 v166, v178
	v_exp_f32_e32 v167, v179
	v_exp_f32_e32 v168, v180
	v_exp_f32_e32 v169, v181
	s_branch .Lret_wdone_30

; #define RET_BAR() do { asm volatile("s_waitcnt lgkmcnt(0)" ::: "memory"); __builtin_amdgcn_s_barrier(); asm volatile("" ::: "memory"); } while (0)
; #define RET_LOADV(t) do { RET_KV(t) const char* vb_ = kb_ + (1024 + h * 256) * 2; const unsigned lo_ = (unsigned)(tid >> 6) * kp_ + (unsigned)(tid & 63) * 16u; \
;         _Pragma("unroll") for (int i_ = 0; i_ < 8; ++i_) vr[i_] = *(const u32x4*)(vb_ + (size_t)(8u * i_) * kp_ + lo_); } while (0)
; #define RET_STOREV() do { _Pragma("unroll") for (int i_ = 0; i_ < 8; ++i_) *(LAS u32x4*)(Vs + ((tid >> 6) + 8 * i_) * 1040 + (tid & 63) * 16) = vr[i_]; } while (0)
; __device__ __forceinline__ void ret_unit(ldsp lds, bf16_t* R, const bf16_t* RC, int b, int h, int qblk, float lgf2, float lgb2, const int tid_in) {
;     ...
;     for (int t = 0; t < 36; ++t) {
;         int tl_ = tid_outer; asm volatile("" : "+v"(tl_));
;         const int tid = tl_, lane = tid & 63, l15 = lane & 15, lg = lane >> 4;
;         if (wid < 4) { RET_PV(t); if (t + 1 < 36) RET_S(t + 1, TI(t + 1)); }
;         else { if (t + 1 < 36) RET_S(t + 1, TI(t + 1)); RET_PV(t); }
;         RET_BAR();
;         asm volatile("s_waitcnt vmcnt(0)" ::: "memory");
;         if (t + 1 < 36) RET_STOREV();
;         if (t + 2 < 36) RET_LOADV(TI(t + 2));
;         if (t + 3 < 36) RET_DMAK(TI(t + 3), (t + 1) & 1);
;         RET_BAR();
.Lret_wdone_30:
	v_mul_f32_e32 v170, v98, v242
	v_mul_f32_e32 v171, v99, v243
	v_mul_f32_e32 v172, v100, v244
	v_mul_f32_e32 v173, v101, v245
	v_cvt_pk_bf16_f32 v174, v170, v171
	v_cvt_pk_bf16_f32 v175, v172, v173
	ds_write_b64 v188, v[174:175] offset:5120
	s_waitcnt vmcnt(6)
	s_add_i32 m0, s55, 8192
	s_nop 0
	global_load_lds_dwordx4 v232, s[42:43]
	s_add_i32 m0, s55, 9216
	s_nop 0
	global_load_lds_dwordx4 v233, s[42:43]
	s_add_i32 m0, s55, 10240
	s_nop 0
	global_load_lds_dwordx4 v234, s[42:43]
	s_add_i32 m0, s55, 11264
	s_nop 0
	global_load_lds_dwordx4 v235, s[42:43]
	ds_read_b64_tr_b16 v[150:151], v183 offset:0
	ds_read_b64_tr_b16 v[152:153], v183 offset:512
	ds_read_b64_tr_b16 v[154:155], v184 offset:0
	ds_read_b64_tr_b16 v[156:157], v184 offset:512
	ds_read_b64_tr_b16 v[158:159], v185 offset:0
	ds_read_b64_tr_b16 v[160:161], v185 offset:512
	ds_read_b64_tr_b16 v[162:163], v186 offset:0
	ds_read_b64_tr_b16 v[164:165], v186 offset:512
	s_waitcnt lgkmcnt(8)
.Lret_regJ_24:
	s_barrier
	s_add_i32 s41, s27, 3
	v_readlane_b32 s42, v238, s41
	v_readlane_b32 s43, v239, s41
	v_readlane_b32 s4, v237, s41
	s_mov_b32 s5, s4
	s_nop 0
	v_cndmask_b32_e64 v230, v191, v189, s[4:5]
	v_cndmask_b32_e64 v231, v192, v190, s[4:5]
	v_cndmask_b32_e64 v232, v198, v193, s[4:5]
	v_cndmask_b32_e64 v233, v199, v194, s[4:5]
	v_cndmask_b32_e64 v234, v200, v195, s[4:5]
	v_cndmask_b32_e64 v235, v202, v197, s[4:5]
	s_add_i32 m0, s54, 0
	s_nop 0
	global_load_lds_dwordx4 v230, s[42:43]
	s_add_i32 m0, s54, 1024
	s_nop 0
	global_load_lds_dwordx4 v231, s[42:43]
	s_cmp_eq_u32 s38, 0
	s_cbranch_scc0 .Lret_regY_31
	ds_read_b128 v[102:105], v182 offset:16384
	ds_read_b128 v[106:109], v246 offset:16384
	ds_read_b128 v[110:113], v247 offset:16384
	ds_read_b128 v[114:117], v248 offset:16384
	ds_read_b128 v[118:121], v182 offset:16640
	ds_read_b128 v[122:125], v246 offset:16640
	ds_read_b128 v[126:129], v247 offset:16640
	ds_read_b128 v[130:133], v248 offset:16640
	ds_read_b128 v[134:137], v187 offset:5120
	ds_read_b128 v[138:141], v187 offset:6400
	ds_read_b128 v[142:145], v187 offset:7680
	ds_read_b128 v[146:149], v187 offset:8960
	s_waitcnt lgkmcnt(11)
	v_mfma_f32_16x16x32_bf16 v[98:101], v[102:105], v[64:67], 0
	s_waitcnt lgkmcnt(10)
	v_mfma_f32_16x16x32_bf16 v[98:101], v[106:109], v[68:71], v[98:101]
	s_waitcnt lgkmcnt(9)
	v_mfma_f32_16x16x32_bf16 v[98:101], v[110:113], v[72:75], v[98:101]
	s_waitcnt lgkmcnt(8)
	v_mfma_f32_16x16x32_bf16 v[98:101], v[114:117], v[76:79], v[98:101]
	s_waitcnt lgkmcnt(7)
	v_mfma_f32_16x16x32_bf16 v[98:101], v[118:121], v[80:83], v[98:101]
	s_waitcnt lgkmcnt(6)
	v_mfma_f32_16x16x32_bf16 v[98:101], v[122:125], v[84:87], v[98:101]
	s_waitcnt lgkmcnt(5)
	v_mfma_f32_16x16x32_bf16 v[98:101], v[126:129], v[88:91], v[98:101]
	s_waitcnt lgkmcnt(4)
	v_mfma_f32_16x16x32_bf16 v[98:101], v[130:133], v[92:95], v[98:101]
	s_waitcnt lgkmcnt(0)
	v_mfma_f32_16x16x32_bf16 v[0:3], v[150:153], v[134:137], v[0:3]
	v_mfma_f32_16x16x32_bf16 v[16:19], v[154:157], v[134:137], v[16:19]
	v_mfma_f32_16x16x32_bf16 v[32:35], v[158:161], v[134:137], v[32:35]
	v_mfma_f32_16x16x32_bf16 v[48:51], v[162:165], v[134:137], v[48:51]
	v_mfma_f32_16x16x32_bf16 v[4:7], v[150:153], v[138:141], v[4:7]
	v_mfma_f32_16x16x32_bf16 v[20:23], v[154:157], v[138:141], v[20:23]
	v_mfma_f32_16x16x32_bf16 v[36:39], v[158:161], v[138:141], v[36:39]
	v_mfma_f32_16x16x32_bf16 v[52:55], v[162:165], v[138:141], v[52:55]
	v_mfma_f32_16x16x32_bf16 v[8:11], v[150:153], v[142:145], v[8:11]
	v_mfma_f32_16x16x32_bf16 v[24:27], v[154:157], v[142:145], v[24:27]
	v_mfma_f32_16x16x32_bf16 v[40:43], v[158:161], v[142:145], v[40:43]
	v_mfma_f32_16x16x32_bf16 v[56:59], v[162:165], v[142:145], v[56:59]
	v_mfma_f32_16x16x32_bf16 v[12:15], v[150:153], v[146:149], v[12:15]
	v_mfma_f32_16x16x32_bf16 v[28:31], v[154:157], v[146:149], v[28:31]
	v_mfma_f32_16x16x32_bf16 v[44:47], v[158:161], v[146:149], v[44:47]
	v_mfma_f32_16x16x32_bf16 v[60:63], v[162:165], v[146:149], v[60:63]
	v_mul_f32_e32 v170, v98, v166
	v_mul_f32_e32 v171, v99, v167
	v_mul_f32_e32 v172, v100, v168
	v_mul_f32_e32 v173, v101, v169
	v_cvt_pk_bf16_f32 v174, v170, v171
	v_cvt_pk_bf16_f32 v175, v172, v173
	ds_write_b64 v188, v[174:175] offset:0
	s_waitcnt vmcnt(6)
	s_add_i32 m0, s55, 0
	s_nop 0
	global_load_lds_dwordx4 v232, s[42:43]
	s_add_i32 m0, s55, 1024
	s_nop 0
	global_load_lds_dwordx4 v233, s[42:43]
	s_add_i32 m0, s55, 2048
	s_nop 0
	global_load_lds_dwordx4 v234, s[42:43]
	s_add_i32 m0, s55, 3072
	s_nop 0
	global_load_lds_dwordx4 v235, s[42:43]
	ds_read_b64_tr_b16 v[150:151], v183 offset:4096
	ds_read_b64_tr_b16 v[152:153], v183 offset:4608
	ds_read_b64_tr_b16 v[154:155], v184 offset:4096
	ds_read_b64_tr_b16 v[156:157], v184 offset:4608
	ds_read_b64_tr_b16 v[158:159], v185 offset:4096
	ds_read_b64_tr_b16 v[160:161], v185 offset:4608
	ds_read_b64_tr_b16 v[162:163], v186 offset:4096
	ds_read_b64_tr_b16 v[164:165], v186 offset:4608
	s_add_i32 s41, s27, 2
	v_readlane_b32 s37, v236, s41
	s_cmp_lt_u32 s37, 32
	s_cbranch_scc0 .Lret_wctx_33
	s_lshl_b32 s100, s37, 6
	s_add_i32 s100, s100, 32
	s_cmp_eq_u32 s37, s9
	s_cbranch_scc1 .Lret_wdiag_34
	s_cmp_lt_u32 s37, s9
	s_cselect_b32 s101, s11, s12
	v_subrev_u32_e32 v170, s100, v203
	v_subrev_u32_e32 v171, s100, v204
	v_subrev_u32_e32 v172, s100, v205
	v_subrev_u32_e32 v173, s100, v206
	v_cvt_f32_i32_e32 v174, v170
	v_cvt_f32_i32_e32 v175, v171
	v_cvt_f32_i32_e32 v176, v172
	v_cvt_f32_i32_e32 v177, v173
	v_mul_f32_e64 v178, s101, |v174|
	v_mul_f32_e64 v179, s101, |v175|
	v_mul_f32_e64 v180, s101, |v176|
	v_mul_f32_e64 v181, s101, |v177|
	v_exp_f32_e32 v242, v178
	v_exp_f32_e32 v243, v179
	v_exp_f32_e32 v244, v180
	v_exp_f32_e32 v245, v181
	s_branch .Lret_wdone_35

; #define RET_BAR() do { asm volatile("s_waitcnt lgkmcnt(0)" ::: "memory"); __builtin_amdgcn_s_barrier(); asm volatile("" ::: "memory"); } while (0)
; #define RET_LOADV(t) do { RET_KV(t) const char* vb_ = kb_ + (1024 + h * 256) * 2; const unsigned lo_ = (unsigned)(tid >> 6) * kp_ + (unsigned)(tid & 63) * 16u; \
;         _Pragma("unroll") for (int i_ = 0; i_ < 8; ++i_) vr[i_] = *(const u32x4*)(vb_ + (size_t)(8u * i_) * kp_ + lo_); } while (0)
; #define RET_STOREV() do { _Pragma("unroll") for (int i_ = 0; i_ < 8; ++i_) *(LAS u32x4*)(Vs + ((tid >> 6) + 8 * i_) * 1040 + (tid & 63) * 16) = vr[i_]; } while (0)
; __device__ __forceinline__ void ret_unit(ldsp lds, bf16_t* R, const bf16_t* RC, int b, int h, int qblk, float lgf2, float lgb2, const int tid_in) {
;     ...
;     for (int t = 0; t < 36; ++t) {
;         int tl_ = tid_outer; asm volatile("" : "+v"(tl_));
;         const int tid = tl_, lane = tid & 63, l15 = lane & 15, lg = lane >> 4;
;         if (wid < 4) { RET_PV(t); if (t + 1 < 36) RET_S(t + 1, TI(t + 1)); }
;         else { if (t + 1 < 36) RET_S(t + 1, TI(t + 1)); RET_PV(t); }
;         RET_BAR();
;         asm volatile("s_waitcnt vmcnt(0)" ::: "memory");
;         if (t + 1 < 36) RET_STOREV();
;         if (t + 2 < 36) RET_LOADV(TI(t + 2));
;         if (t + 3 < 36) RET_DMAK(TI(t + 3), (t + 1) & 1);
;         RET_BAR();
.Lret_wdone_38:
	v_mul_f32_e32 v170, v98, v166
	v_mul_f32_e32 v171, v99, v167
	v_mul_f32_e32 v172, v100, v168
	v_mul_f32_e32 v173, v101, v169
	v_cvt_pk_bf16_f32 v174, v170, v171
	v_cvt_pk_bf16_f32 v175, v172, v173
	ds_write_b64 v188, v[174:175] offset:0
	s_waitcnt vmcnt(6)
	s_add_i32 m0, s55, 0
	s_nop 0
	global_load_lds_dwordx4 v232, s[42:43]
	s_add_i32 m0, s55, 1024
	s_nop 0
	global_load_lds_dwordx4 v233, s[42:43]
	s_add_i32 m0, s55, 2048
	s_nop 0
	global_load_lds_dwordx4 v234, s[42:43]
	s_add_i32 m0, s55, 3072
	s_nop 0
	global_load_lds_dwordx4 v235, s[42:43]
	ds_read_b64_tr_b16 v[150:151], v183 offset:4096
	ds_read_b64_tr_b16 v[152:153], v183 offset:4608
	ds_read_b64_tr_b16 v[154:155], v184 offset:4096
	ds_read_b64_tr_b16 v[156:157], v184 offset:4608
	ds_read_b64_tr_b16 v[158:159], v185 offset:4096
	ds_read_b64_tr_b16 v[160:161], v185 offset:4608
	ds_read_b64_tr_b16 v[162:163], v186 offset:4096
	ds_read_b64_tr_b16 v[164:165], v186 offset:4608
	s_waitcnt lgkmcnt(8)
.Lret_regJ_32:
	s_barrier
	s_add_i32 s41, s27, 3
	v_readlane_b32 s42, v240, s41
	v_readlane_b32 s43, v241, s41
	v_readlane_b32 s4, v237, s41
	s_mov_b32 s5, s4
	s_nop 0
	v_cndmask_b32_e64 v230, v191, v189, s[4:5]
	v_cndmask_b32_e64 v231, v192, v190, s[4:5]
	v_cndmask_b32_e64 v232, v198, v193, s[4:5]
	v_cndmask_b32_e64 v233, v199, v194, s[4:5]
	v_cndmask_b32_e64 v234, v200, v195, s[4:5]
	v_cndmask_b32_e64 v235, v202, v197, s[4:5]
	s_add_i32 m0, s54, 16384
	s_nop 0
	global_load_lds_dwordx4 v230, s[42:43]
	s_add_i32 m0, s54, 17408
	s_nop 0
	global_load_lds_dwordx4 v231, s[42:43]
	s_cmp_eq_u32 s38, 0
	s_cbranch_scc0 .Lret_regY_39
	ds_read_b128 v[102:105], v182 offset:32768
	ds_read_b128 v[106:109], v246 offset:32768
	ds_read_b128 v[110:113], v247 offset:32768
	ds_read_b128 v[114:117], v248 offset:32768
	ds_read_b128 v[118:121], v182 offset:33024
	ds_read_b128 v[122:125], v246 offset:33024
	ds_read_b128 v[126:129], v247 offset:33024
	ds_read_b128 v[130:133], v248 offset:33024
	ds_read_b128 v[134:137], v187 offset:0
	ds_read_b128 v[138:141], v187 offset:1280
	ds_read_b128 v[142:145], v187 offset:2560
	ds_read_b128 v[146:149], v187 offset:3840
	s_waitcnt lgkmcnt(11)
	v_mfma_f32_16x16x32_bf16 v[98:101], v[102:105], v[64:67], 0
	s_waitcnt lgkmcnt(10)
	v_mfma_f32_16x16x32_bf16 v[98:101], v[106:109], v[68:71], v[98:101]
	s_waitcnt lgkmcnt(9)
	v_mfma_f32_16x16x32_bf16 v[98:101], v[110:113], v[72:75], v[98:101]
	s_waitcnt lgkmcnt(8)
	v_mfma_f32_16x16x32_bf16 v[98:101], v[114:117], v[76:79], v[98:101]
	s_waitcnt lgkmcnt(7)
	v_mfma_f32_16x16x32_bf16 v[98:101], v[118:121], v[80:83], v[98:101]
	s_waitcnt lgkmcnt(6)
	v_mfma_f32_16x16x32_bf16 v[98:101], v[122:125], v[84:87], v[98:101]
	s_waitcnt lgkmcnt(5)
	v_mfma_f32_16x16x32_bf16 v[98:101], v[126:129], v[88:91], v[98:101]
	s_waitcnt lgkmcnt(4)
	v_mfma_f32_16x16x32_bf16 v[98:101], v[130:133], v[92:95], v[98:101]
	s_waitcnt lgkmcnt(0)
	v_mfma_f32_16x16x32_bf16 v[0:3], v[150:153], v[134:137], v[0:3]
	v_mfma_f32_16x16x32_bf16 v[16:19], v[154:157], v[134:137], v[16:19]
	v_mfma_f32_16x16x32_bf16 v[32:35], v[158:161], v[134:137], v[32:35]
	v_mfma_f32_16x16x32_bf16 v[48:51], v[162:165], v[134:137], v[48:51]
	v_mfma_f32_16x16x32_bf16 v[4:7], v[150:153], v[138:141], v[4:7]
	v_mfma_f32_16x16x32_bf16 v[20:23], v[154:157], v[138:141], v[20:23]
	v_mfma_f32_16x16x32_bf16 v[36:39], v[158:161], v[138:141], v[36:39]
	v_mfma_f32_16x16x32_bf16 v[52:55], v[162:165], v[138:141], v[52:55]
	v_mfma_f32_16x16x32_bf16 v[8:11], v[150:153], v[142:145], v[8:11]
	v_mfma_f32_16x16x32_bf16 v[24:27], v[154:157], v[142:145], v[24:27]
	v_mfma_f32_16x16x32_bf16 v[40:43], v[158:161], v[142:145], v[40:43]
	v_mfma_f32_16x16x32_bf16 v[56:59], v[162:165], v[142:145], v[56:59]
	v_mfma_f32_16x16x32_bf16 v[12:15], v[150:153], v[146:149], v[12:15]
	v_mfma_f32_16x16x32_bf16 v[28:31], v[154:157], v[146:149], v[28:31]
	v_mfma_f32_16x16x32_bf16 v[44:47], v[158:161], v[146:149], v[44:47]
	v_mfma_f32_16x16x32_bf16 v[60:63], v[162:165], v[146:149], v[60:63]
	v_mul_f32_e32 v170, v98, v242
	v_mul_f32_e32 v171, v99, v243
	v_mul_f32_e32 v172, v100, v244
	v_mul_f32_e32 v173, v101, v245
	v_cvt_pk_bf16_f32 v174, v170, v171
	v_cvt_pk_bf16_f32 v175, v172, v173
	ds_write_b64 v188, v[174:175] offset:5120
	s_waitcnt vmcnt(6)
	s_add_i32 m0, s55, 4096
	s_nop 0
	global_load_lds_dwordx4 v232, s[42:43]
	s_add_i32 m0, s55, 5120
	s_nop 0
	global_load_lds_dwordx4 v233, s[42:43]
	s_add_i32 m0, s55, 6144
	s_nop 0
	global_load_lds_dwordx4 v234, s[42:43]
	s_add_i32 m0, s55, 7168
	s_nop 0
	global_load_lds_dwordx4 v235, s[42:43]
	ds_read_b64_tr_b16 v[150:151], v183 offset:8192
	ds_read_b64_tr_b16 v[152:153], v183 offset:8704
	ds_read_b64_tr_b16 v[154:155], v184 offset:8192
	ds_read_b64_tr_b16 v[156:157], v184 offset:8704
	ds_read_b64_tr_b16 v[158:159], v185 offset:8192
	ds_read_b64_tr_b16 v[160:161], v185 offset:8704
	ds_read_b64_tr_b16 v[162:163], v186 offset:8192
	ds_read_b64_tr_b16 v[164:165], v186 offset:8704
	s_add_i32 s41, s27, 3
	v_readlane_b32 s37, v236, s41
	s_cmp_lt_u32 s37, 32
	s_cbranch_scc0 .Lret_wctx_41
	s_lshl_b32 s100, s37, 6
	s_cmp_eq_u32 s37, s9
	s_cbranch_scc1 .Lret_wdiag_42
	s_cmp_lt_u32 s37, s9
	s_cselect_b32 s101, s11, s12
	v_subrev_u32_e32 v170, s100, v203
	v_subrev_u32_e32 v171, s100, v204
	v_subrev_u32_e32 v172, s100, v205
	v_subrev_u32_e32 v173, s100, v206
	v_cvt_f32_i32_e32 v174, v170
	v_cvt_f32_i32_e32 v175, v171
	v_cvt_f32_i32_e32 v176, v172
	v_cvt_f32_i32_e32 v177, v173
	v_mul_f32_e64 v178, s101, |v174|
	v_mul_f32_e64 v179, s101, |v175|
	v_mul_f32_e64 v180, s101, |v176|
	v_mul_f32_e64 v181, s101, |v177|
	v_exp_f32_e32 v166, v178
	v_exp_f32_e32 v167, v179
	v_exp_f32_e32 v168, v180
	v_exp_f32_e32 v169, v181
	s_branch .Lret_wdone_43

; __device__ __forceinline__ void ret_unit(ldsp lds, bf16_t* R, const bf16_t* RC, int b, int h, int qblk, float lgf2, float lgb2, const int tid_in) {
;     ...
;         else { if (t + 1 < 36) RET_S(t + 1, TI(t + 1)); RET_PV(t); }
.Lret_regY_39:
	ds_read_b128 v[134:137], v187 offset:0
	ds_read_b128 v[138:141], v187 offset:1280
	ds_read_b128 v[142:145], v187 offset:2560
	ds_read_b128 v[146:149], v187 offset:3840
	ds_read_b128 v[102:105], v182 offset:32768
	ds_read_b128 v[106:109], v246 offset:32768
	ds_read_b128 v[110:113], v247 offset:32768
	ds_read_b128 v[114:117], v248 offset:32768
	ds_read_b128 v[118:121], v182 offset:33024
	ds_read_b128 v[122:125], v246 offset:33024
	ds_read_b128 v[126:129], v247 offset:33024
	ds_read_b128 v[130:133], v248 offset:33024
	s_waitcnt lgkmcnt(8)
	v_mfma_f32_16x16x32_bf16 v[0:3], v[150:153], v[134:137], v[0:3]
	v_mfma_f32_16x16x32_bf16 v[16:19], v[154:157], v[134:137], v[16:19]
	v_mfma_f32_16x16x32_bf16 v[32:35], v[158:161], v[134:137], v[32:35]
	v_mfma_f32_16x16x32_bf16 v[48:51], v[162:165], v[134:137], v[48:51]
	v_mfma_f32_16x16x32_bf16 v[4:7], v[150:153], v[138:141], v[4:7]
	v_mfma_f32_16x16x32_bf16 v[20:23], v[154:157], v[138:141], v[20:23]
	v_mfma_f32_16x16x32_bf16 v[36:39], v[158:161], v[138:141], v[36:39]
	v_mfma_f32_16x16x32_bf16 v[52:55], v[162:165], v[138:141], v[52:55]
	v_mfma_f32_16x16x32_bf16 v[8:11], v[150:153], v[142:145], v[8:11]
	v_mfma_f32_16x16x32_bf16 v[24:27], v[154:157], v[142:145], v[24:27]
	v_mfma_f32_16x16x32_bf16 v[40:43], v[158:161], v[142:145], v[40:43]
	v_mfma_f32_16x16x32_bf16 v[56:59], v[162:165], v[142:145], v[56:59]
	v_mfma_f32_16x16x32_bf16 v[12:15], v[150:153], v[146:149], v[12:15]
	v_mfma_f32_16x16x32_bf16 v[28:31], v[154:157], v[146:149], v[28:31]
	v_mfma_f32_16x16x32_bf16 v[44:47], v[158:161], v[146:149], v[44:47]
	v_mfma_f32_16x16x32_bf16 v[60:63], v[162:165], v[146:149], v[60:63]
	s_waitcnt lgkmcnt(7)
	v_mfma_f32_16x16x32_bf16 v[98:101], v[102:105], v[64:67], 0
	s_waitcnt lgkmcnt(6)
	v_mfma_f32_16x16x32_bf16 v[98:101], v[106:109], v[68:71], v[98:101]
	s_waitcnt lgkmcnt(5)
	v_mfma_f32_16x16x32_bf16 v[98:101], v[110:113], v[72:75], v[98:101]
	s_waitcnt lgkmcnt(4)
	v_mfma_f32_16x16x32_bf16 v[98:101], v[114:117], v[76:79], v[98:101]
	s_waitcnt lgkmcnt(3)
	v_mfma_f32_16x16x32_bf16 v[98:101], v[118:121], v[80:83], v[98:101]
	s_waitcnt lgkmcnt(2)
	v_mfma_f32_16x16x32_bf16 v[98:101], v[122:125], v[84:87], v[98:101]
	s_waitcnt lgkmcnt(1)
	v_mfma_f32_16x16x32_bf16 v[98:101], v[126:129], v[88:91], v[98:101]
	s_waitcnt lgkmcnt(0)
	v_mfma_f32_16x16x32_bf16 v[98:101], v[130:133], v[92:95], v[98:101]
	s_add_i32 s41, s27, 3
	v_readlane_b32 s37, v236, s41
	s_cmp_lt_u32 s37, 32
	s_cbranch_scc0 .Lret_wctx_44
	s_lshl_b32 s100, s37, 6
	s_cmp_eq_u32 s37, s9
	s_cbranch_scc1 .Lret_wdiag_45
	s_cmp_lt_u32 s37, s9
	s_cselect_b32 s101, s11, s12
	v_subrev_u32_e32 v170, s100, v203
	v_subrev_u32_e32 v171, s100, v204
	v_subrev_u32_e32 v172, s100, v205
	v_subrev_u32_e32 v173, s100, v206
	v_cvt_f32_i32_e32 v174, v170
	v_cvt_f32_i32_e32 v175, v171
	v_cvt_f32_i32_e32 v176, v172
	v_cvt_f32_i32_e32 v177, v173
	v_mul_f32_e64 v178, s101, |v174|
	v_mul_f32_e64 v179, s101, |v175|
	v_mul_f32_e64 v180, s101, |v176|
	v_mul_f32_e64 v181, s101, |v177|
	v_exp_f32_e32 v166, v178
	v_exp_f32_e32 v167, v179
	v_exp_f32_e32 v168, v180
	v_exp_f32_e32 v169, v181
	s_branch .Lret_wdone_46

; #define RET_BAR() do { asm volatile("s_waitcnt lgkmcnt(0)" ::: "memory"); __builtin_amdgcn_s_barrier(); asm volatile("" ::: "memory"); } while (0)
; #define RET_LOADV(t) do { RET_KV(t) const char* vb_ = kb_ + (1024 + h * 256) * 2; const unsigned lo_ = (unsigned)(tid >> 6) * kp_ + (unsigned)(tid & 63) * 16u; \
;         _Pragma("unroll") for (int i_ = 0; i_ < 8; ++i_) vr[i_] = *(const u32x4*)(vb_ + (size_t)(8u * i_) * kp_ + lo_); } while (0)
; #define RET_STOREV() do { _Pragma("unroll") for (int i_ = 0; i_ < 8; ++i_) *(LAS u32x4*)(Vs + ((tid >> 6) + 8 * i_) * 1040 + (tid & 63) * 16) = vr[i_]; } while (0)
; __device__ __forceinline__ void ret_unit(ldsp lds, bf16_t* R, const bf16_t* RC, int b, int h, int qblk, float lgf2, float lgb2, const int tid_in) {
;     ...
;     for (int t = 0; t < 36; ++t) {
;         int tl_ = tid_outer; asm volatile("" : "+v"(tl_));
;         const int tid = tl_, lane = tid & 63, l15 = lane & 15, lg = lane >> 4;
;         if (wid < 4) { RET_PV(t); if (t + 1 < 36) RET_S(t + 1, TI(t + 1)); }
;         else { if (t + 1 < 36) RET_S(t + 1, TI(t + 1)); RET_PV(t); }
;         RET_BAR();
;         asm volatile("s_waitcnt vmcnt(0)" ::: "memory");
;         if (t + 1 < 36) RET_STOREV();
;         if (t + 2 < 36) RET_LOADV(TI(t + 2));
;         if (t + 3 < 36) RET_DMAK(TI(t + 3), (t + 1) & 1);
;         RET_BAR();
.Lret_wdone_46:
	v_mul_f32_e32 v170, v98, v242
	v_mul_f32_e32 v171, v99, v243
	v_mul_f32_e32 v172, v100, v244
	v_mul_f32_e32 v173, v101, v245
	v_cvt_pk_bf16_f32 v174, v170, v171
	v_cvt_pk_bf16_f32 v175, v172, v173
	ds_write_b64 v188, v[174:175] offset:5120
	s_waitcnt vmcnt(6)
	s_add_i32 m0, s55, 4096
	s_nop 0
	global_load_lds_dwordx4 v232, s[42:43]
	s_add_i32 m0, s55, 5120
	s_nop 0
	global_load_lds_dwordx4 v233, s[42:43]
	s_add_i32 m0, s55, 6144
	s_nop 0
	global_load_lds_dwordx4 v234, s[42:43]
	s_add_i32 m0, s55, 7168
	s_nop 0
	global_load_lds_dwordx4 v235, s[42:43]
	ds_read_b64_tr_b16 v[150:151], v183 offset:8192
	ds_read_b64_tr_b16 v[152:153], v183 offset:8704
	ds_read_b64_tr_b16 v[154:155], v184 offset:8192
	ds_read_b64_tr_b16 v[156:157], v184 offset:8704
	ds_read_b64_tr_b16 v[158:159], v185 offset:8192
	ds_read_b64_tr_b16 v[160:161], v185 offset:8704
	ds_read_b64_tr_b16 v[162:163], v186 offset:8192
	ds_read_b64_tr_b16 v[164:165], v186 offset:8704
	s_waitcnt lgkmcnt(8)
.Lret_regJ_40:
	s_barrier
	s_add_i32 s41, s27, 4
	v_readlane_b32 s42, v238, s41
	v_readlane_b32 s43, v239, s41
	v_readlane_b32 s4, v237, s41
	s_mov_b32 s5, s4
	s_nop 0
	v_cndmask_b32_e64 v230, v191, v189, s[4:5]
	v_cndmask_b32_e64 v231, v192, v190, s[4:5]
	v_cndmask_b32_e64 v232, v198, v193, s[4:5]
	v_cndmask_b32_e64 v233, v199, v194, s[4:5]
	v_cndmask_b32_e64 v234, v200, v195, s[4:5]
	v_cndmask_b32_e64 v235, v202, v197, s[4:5]
	s_add_i32 m0, s54, 32768
	s_nop 0
	global_load_lds_dwordx4 v230, s[42:43]
	s_add_i32 m0, s54, 33792
	s_nop 0
	global_load_lds_dwordx4 v231, s[42:43]
	s_cmp_eq_u32 s38, 0
	s_cbranch_scc0 .Lret_regY_47
	ds_read_b128 v[102:105], v182 offset:0
	ds_read_b128 v[106:109], v246 offset:0
	ds_read_b128 v[110:113], v247 offset:0
	ds_read_b128 v[114:117], v248 offset:0
	ds_read_b128 v[118:121], v182 offset:256
	ds_read_b128 v[122:125], v246 offset:256
	ds_read_b128 v[126:129], v247 offset:256
	ds_read_b128 v[130:133], v248 offset:256
	ds_read_b128 v[134:137], v187 offset:5120
	ds_read_b128 v[138:141], v187 offset:6400
	ds_read_b128 v[142:145], v187 offset:7680
	ds_read_b128 v[146:149], v187 offset:8960
	s_waitcnt lgkmcnt(11)
	v_mfma_f32_16x16x32_bf16 v[98:101], v[102:105], v[64:67], 0
	s_waitcnt lgkmcnt(10)
	v_mfma_f32_16x16x32_bf16 v[98:101], v[106:109], v[68:71], v[98:101]
	s_waitcnt lgkmcnt(9)
	v_mfma_f32_16x16x32_bf16 v[98:101], v[110:113], v[72:75], v[98:101]
	s_waitcnt lgkmcnt(8)
	v_mfma_f32_16x16x32_bf16 v[98:101], v[114:117], v[76:79], v[98:101]
	s_waitcnt lgkmcnt(7)
	v_mfma_f32_16x16x32_bf16 v[98:101], v[118:121], v[80:83], v[98:101]
	s_waitcnt lgkmcnt(6)
	v_mfma_f32_16x16x32_bf16 v[98:101], v[122:125], v[84:87], v[98:101]
	s_waitcnt lgkmcnt(5)
	v_mfma_f32_16x16x32_bf16 v[98:101], v[126:129], v[88:91], v[98:101]
	s_waitcnt lgkmcnt(4)
	v_mfma_f32_16x16x32_bf16 v[98:101], v[130:133], v[92:95], v[98:101]
	s_waitcnt lgkmcnt(0)
	v_mfma_f32_16x16x32_bf16 v[0:3], v[150:153], v[134:137], v[0:3]
	v_mfma_f32_16x16x32_bf16 v[16:19], v[154:157], v[134:137], v[16:19]
	v_mfma_f32_16x16x32_bf16 v[32:35], v[158:161], v[134:137], v[32:35]
	v_mfma_f32_16x16x32_bf16 v[48:51], v[162:165], v[134:137], v[48:51]
	v_mfma_f32_16x16x32_bf16 v[4:7], v[150:153], v[138:141], v[4:7]
	v_mfma_f32_16x16x32_bf16 v[20:23], v[154:157], v[138:141], v[20:23]
	v_mfma_f32_16x16x32_bf16 v[36:39], v[158:161], v[138:141], v[36:39]
	v_mfma_f32_16x16x32_bf16 v[52:55], v[162:165], v[138:141], v[52:55]
	v_mfma_f32_16x16x32_bf16 v[8:11], v[150:153], v[142:145], v[8:11]
	v_mfma_f32_16x16x32_bf16 v[24:27], v[154:157], v[142:145], v[24:27]
	v_mfma_f32_16x16x32_bf16 v[40:43], v[158:161], v[142:145], v[40:43]
	v_mfma_f32_16x16x32_bf16 v[56:59], v[162:165], v[142:145], v[56:59]
	v_mfma_f32_16x16x32_bf16 v[12:15], v[150:153], v[146:149], v[12:15]
	v_mfma_f32_16x16x32_bf16 v[28:31], v[154:157], v[146:149], v[28:31]
	v_mfma_f32_16x16x32_bf16 v[44:47], v[158:161], v[146:149], v[44:47]
	v_mfma_f32_16x16x32_bf16 v[60:63], v[162:165], v[146:149], v[60:63]
	v_mul_f32_e32 v170, v98, v166
	v_mul_f32_e32 v171, v99, v167
	v_mul_f32_e32 v172, v100, v168
	v_mul_f32_e32 v173, v101, v169
	v_cvt_pk_bf16_f32 v174, v170, v171
	v_cvt_pk_bf16_f32 v175, v172, v173
	ds_write_b64 v188, v[174:175] offset:0
	s_waitcnt vmcnt(6)
	s_add_i32 m0, s55, 8192
	s_nop 0
	global_load_lds_dwordx4 v232, s[42:43]
	s_add_i32 m0, s55, 9216
	s_nop 0
	global_load_lds_dwordx4 v233, s[42:43]
	s_add_i32 m0, s55, 10240
	s_nop 0
	global_load_lds_dwordx4 v234, s[42:43]
	s_add_i32 m0, s55, 11264
	s_nop 0
	global_load_lds_dwordx4 v235, s[42:43]
	ds_read_b64_tr_b16 v[150:151], v183 offset:0
	ds_read_b64_tr_b16 v[152:153], v183 offset:512
	ds_read_b64_tr_b16 v[154:155], v184 offset:0
	ds_read_b64_tr_b16 v[156:157], v184 offset:512
	ds_read_b64_tr_b16 v[158:159], v185 offset:0
	ds_read_b64_tr_b16 v[160:161], v185 offset:512
	ds_read_b64_tr_b16 v[162:163], v186 offset:0
	ds_read_b64_tr_b16 v[164:165], v186 offset:512
	s_add_i32 s41, s27, 3
	v_readlane_b32 s37, v236, s41
	s_cmp_lt_u32 s37, 32
	s_cbranch_scc0 .Lret_wctx_49
	s_lshl_b32 s100, s37, 6
	s_add_i32 s100, s100, 32
	s_cmp_eq_u32 s37, s9
	s_cbranch_scc1 .Lret_wdiag_50
	s_cmp_lt_u32 s37, s9
	s_cselect_b32 s101, s11, s12
	v_subrev_u32_e32 v170, s100, v203
	v_subrev_u32_e32 v171, s100, v204
	v_subrev_u32_e32 v172, s100, v205
	v_subrev_u32_e32 v173, s100, v206
	v_cvt_f32_i32_e32 v174, v170
	v_cvt_f32_i32_e32 v175, v171
	v_cvt_f32_i32_e32 v176, v172
	v_cvt_f32_i32_e32 v177, v173
	v_mul_f32_e64 v178, s101, |v174|
	v_mul_f32_e64 v179, s101, |v175|
	v_mul_f32_e64 v180, s101, |v176|
	v_mul_f32_e64 v181, s101, |v177|
	v_exp_f32_e32 v242, v178
	v_exp_f32_e32 v243, v179
	v_exp_f32_e32 v244, v180
	v_exp_f32_e32 v245, v181
	s_branch .Lret_wdone_51

.Lret_regY_47:
	ds_read_b128 v[134:137], v187 offset:5120
	ds_read_b128 v[138:141], v187 offset:6400
	ds_read_b128 v[142:145], v187 offset:7680
	ds_read_b128 v[146:149], v187 offset:8960
	ds_read_b128 v[102:105], v182 offset:0
	ds_read_b128 v[106:109], v246 offset:0
	ds_read_b128 v[110:113], v247 offset:0
	ds_read_b128 v[114:117], v248 offset:0
	ds_read_b128 v[118:121], v182 offset:256
	ds_read_b128 v[122:125], v246 offset:256
	ds_read_b128 v[126:129], v247 offset:256
	ds_read_b128 v[130:133], v248 offset:256
	s_waitcnt lgkmcnt(8)
	v_mfma_f32_16x16x32_bf16 v[0:3], v[150:153], v[134:137], v[0:3]
	v_mfma_f32_16x16x32_bf16 v[16:19], v[154:157], v[134:137], v[16:19]
	v_mfma_f32_16x16x32_bf16 v[32:35], v[158:161], v[134:137], v[32:35]
	v_mfma_f32_16x16x32_bf16 v[48:51], v[162:165], v[134:137], v[48:51]
	v_mfma_f32_16x16x32_bf16 v[4:7], v[150:153], v[138:141], v[4:7]
	v_mfma_f32_16x16x32_bf16 v[20:23], v[154:157], v[138:141], v[20:23]
	v_mfma_f32_16x16x32_bf16 v[36:39], v[158:161], v[138:141], v[36:39]
	v_mfma_f32_16x16x32_bf16 v[52:55], v[162:165], v[138:141], v[52:55]
	v_mfma_f32_16x16x32_bf16 v[8:11], v[150:153], v[142:145], v[8:11]
	v_mfma_f32_16x16x32_bf16 v[24:27], v[154:157], v[142:145], v[24:27]
	v_mfma_f32_16x16x32_bf16 v[40:43], v[158:161], v[142:145], v[40:43]
	v_mfma_f32_16x16x32_bf16 v[56:59], v[162:165], v[142:145], v[56:59]
	v_mfma_f32_16x16x32_bf16 v[12:15], v[150:153], v[146:149], v[12:15]
	v_mfma_f32_16x16x32_bf16 v[28:31], v[154:157], v[146:149], v[28:31]
	v_mfma_f32_16x16x32_bf16 v[44:47], v[158:161], v[146:149], v[44:47]
	v_mfma_f32_16x16x32_bf16 v[60:63], v[162:165], v[146:149], v[60:63]
	s_waitcnt lgkmcnt(7)
	v_mfma_f32_16x16x32_bf16 v[98:101], v[102:105], v[64:67], 0
	s_waitcnt lgkmcnt(6)
	v_mfma_f32_16x16x32_bf16 v[98:101], v[106:109], v[68:71], v[98:101]
	s_waitcnt lgkmcnt(5)
	v_mfma_f32_16x16x32_bf16 v[98:101], v[110:113], v[72:75], v[98:101]
	s_waitcnt lgkmcnt(4)
	v_mfma_f32_16x16x32_bf16 v[98:101], v[114:117], v[76:79], v[98:101]
	s_waitcnt lgkmcnt(3)
	v_mfma_f32_16x16x32_bf16 v[98:101], v[118:121], v[80:83], v[98:101]
	s_waitcnt lgkmcnt(2)
	v_mfma_f32_16x16x32_bf16 v[98:101], v[122:125], v[84:87], v[98:101]
	s_waitcnt lgkmcnt(1)
	v_mfma_f32_16x16x32_bf16 v[98:101], v[126:129], v[88:91], v[98:101]
	s_waitcnt lgkmcnt(0)
	v_mfma_f32_16x16x32_bf16 v[98:101], v[130:133], v[92:95], v[98:101]
	s_add_i32 s41, s27, 3
	v_readlane_b32 s37, v236, s41
	s_cmp_lt_u32 s37, 32
	s_cbranch_scc0 .Lret_wctx_52
	s_lshl_b32 s100, s37, 6
	s_add_i32 s100, s100, 32
	s_cmp_eq_u32 s37, s9
	s_cbranch_scc1 .Lret_wdiag_53
	s_cmp_lt_u32 s37, s9
	s_cselect_b32 s101, s11, s12
	v_subrev_u32_e32 v170, s100, v203
	v_subrev_u32_e32 v171, s100, v204
	v_subrev_u32_e32 v172, s100, v205
	v_subrev_u32_e32 v173, s100, v206
	v_cvt_f32_i32_e32 v174, v170
	v_cvt_f32_i32_e32 v175, v171
	v_cvt_f32_i32_e32 v176, v172
	v_cvt_f32_i32_e32 v177, v173
	v_mul_f32_e64 v178, s101, |v174|
	v_mul_f32_e64 v179, s101, |v175|
	v_mul_f32_e64 v180, s101, |v176|
	v_mul_f32_e64 v181, s101, |v177|
	v_exp_f32_e32 v242, v178
	v_exp_f32_e32 v243, v179
	v_exp_f32_e32 v244, v180
	v_exp_f32_e32 v245, v181
	s_branch .Lret_wdone_54

; #define RET_BAR() do { asm volatile("s_waitcnt lgkmcnt(0)" ::: "memory"); __builtin_amdgcn_s_barrier(); asm volatile("" ::: "memory"); } while (0)
; #define RET_LOADV(t) do { RET_KV(t) const char* vb_ = kb_ + (1024 + h * 256) * 2; const unsigned lo_ = (unsigned)(tid >> 6) * kp_ + (unsigned)(tid & 63) * 16u; \
;         _Pragma("unroll") for (int i_ = 0; i_ < 8; ++i_) vr[i_] = *(const u32x4*)(vb_ + (size_t)(8u * i_) * kp_ + lo_); } while (0)
; #define RET_STOREV() do { _Pragma("unroll") for (int i_ = 0; i_ < 8; ++i_) *(LAS u32x4*)(Vs + ((tid >> 6) + 8 * i_) * 1040 + (tid & 63) * 16) = vr[i_]; } while (0)
; __device__ __forceinline__ void ret_unit(ldsp lds, bf16_t* R, const bf16_t* RC, int b, int h, int qblk, float lgf2, float lgb2, const int tid_in) {
;     ...
;     for (int t = 0; t < 36; ++t) {
;         int tl_ = tid_outer; asm volatile("" : "+v"(tl_));
;         const int tid = tl_, lane = tid & 63, l15 = lane & 15, lg = lane >> 4;
;         if (wid < 4) { RET_PV(t); if (t + 1 < 36) RET_S(t + 1, TI(t + 1)); }
;         else { if (t + 1 < 36) RET_S(t + 1, TI(t + 1)); RET_PV(t); }
;         RET_BAR();
;         asm volatile("s_waitcnt vmcnt(0)" ::: "memory");
;         if (t + 1 < 36) RET_STOREV();
;         if (t + 2 < 36) RET_LOADV(TI(t + 2));
;         if (t + 3 < 36) RET_DMAK(TI(t + 3), (t + 1) & 1);
;         RET_BAR();
.Lret_wdone_54:
	v_mul_f32_e32 v170, v98, v166
	v_mul_f32_e32 v171, v99, v167
	v_mul_f32_e32 v172, v100, v168
	v_mul_f32_e32 v173, v101, v169
	v_cvt_pk_bf16_f32 v174, v170, v171
	v_cvt_pk_bf16_f32 v175, v172, v173
	ds_write_b64 v188, v[174:175] offset:0
	s_waitcnt vmcnt(6)
	s_add_i32 m0, s55, 8192
	s_nop 0
	global_load_lds_dwordx4 v232, s[42:43]
	s_add_i32 m0, s55, 9216
	s_nop 0
	global_load_lds_dwordx4 v233, s[42:43]
	s_add_i32 m0, s55, 10240
	s_nop 0
	global_load_lds_dwordx4 v234, s[42:43]
	s_add_i32 m0, s55, 11264
	s_nop 0
	global_load_lds_dwordx4 v235, s[42:43]
	ds_read_b64_tr_b16 v[150:151], v183 offset:0
	ds_read_b64_tr_b16 v[152:153], v183 offset:512
	ds_read_b64_tr_b16 v[154:155], v184 offset:0
	ds_read_b64_tr_b16 v[156:157], v184 offset:512
	ds_read_b64_tr_b16 v[158:159], v185 offset:0
	ds_read_b64_tr_b16 v[160:161], v185 offset:512
	ds_read_b64_tr_b16 v[162:163], v186 offset:0
	ds_read_b64_tr_b16 v[164:165], v186 offset:512
	s_waitcnt lgkmcnt(8)
.Lret_regJ_48:
	s_barrier
	s_add_i32 s27, s27, 3
	s_cmp_lt_u32 s27, 33
	s_cbranch_scc1 .Lret_loop
	s_add_i32 s41, s27, 1
	v_readlane_b32 s42, v240, s41
	v_readlane_b32 s43, v241, s41
	v_readlane_b32 s4, v237, s41
	s_mov_b32 s5, s4
	s_nop 0
	v_cndmask_b32_e64 v230, v191, v189, s[4:5]
	v_cndmask_b32_e64 v231, v192, v190, s[4:5]
	v_cndmask_b32_e64 v232, v198, v193, s[4:5]
	v_cndmask_b32_e64 v233, v199, v194, s[4:5]
	v_cndmask_b32_e64 v234, v200, v195, s[4:5]
	v_cndmask_b32_e64 v235, v202, v197, s[4:5]
	s_add_i32 m0, s54, 0
	s_nop 0
	global_load_lds_dwordx4 v230, s[42:43]
	s_add_i32 m0, s54, 1024
	s_nop 0
	global_load_lds_dwordx4 v231, s[42:43]
	s_cmp_eq_u32 s38, 0
	s_cbranch_scc0 .Lret_regY_55
	ds_read_b128 v[102:105], v182 offset:16384
	ds_read_b128 v[106:109], v246 offset:16384
	ds_read_b128 v[110:113], v247 offset:16384
	ds_read_b128 v[114:117], v248 offset:16384
	ds_read_b128 v[118:121], v182 offset:16640
	ds_read_b128 v[122:125], v246 offset:16640
	ds_read_b128 v[126:129], v247 offset:16640
	ds_read_b128 v[130:133], v248 offset:16640
	ds_read_b128 v[134:137], v187 offset:0
	ds_read_b128 v[138:141], v187 offset:1280
	ds_read_b128 v[142:145], v187 offset:2560
	ds_read_b128 v[146:149], v187 offset:3840
	s_waitcnt lgkmcnt(11)
	v_mfma_f32_16x16x32_bf16 v[98:101], v[102:105], v[64:67], 0
	s_waitcnt lgkmcnt(10)
	v_mfma_f32_16x16x32_bf16 v[98:101], v[106:109], v[68:71], v[98:101]
	s_waitcnt lgkmcnt(9)
	v_mfma_f32_16x16x32_bf16 v[98:101], v[110:113], v[72:75], v[98:101]
	s_waitcnt lgkmcnt(8)
	v_mfma_f32_16x16x32_bf16 v[98:101], v[114:117], v[76:79], v[98:101]
	s_waitcnt lgkmcnt(7)
	v_mfma_f32_16x16x32_bf16 v[98:101], v[118:121], v[80:83], v[98:101]
	s_waitcnt lgkmcnt(6)
	v_mfma_f32_16x16x32_bf16 v[98:101], v[122:125], v[84:87], v[98:101]
	s_waitcnt lgkmcnt(5)
	v_mfma_f32_16x16x32_bf16 v[98:101], v[126:129], v[88:91], v[98:101]
	s_waitcnt lgkmcnt(4)
	v_mfma_f32_16x16x32_bf16 v[98:101], v[130:133], v[92:95], v[98:101]
	s_waitcnt lgkmcnt(0)
	v_mfma_f32_16x16x32_bf16 v[0:3], v[150:153], v[134:137], v[0:3]
	v_mfma_f32_16x16x32_bf16 v[16:19], v[154:157], v[134:137], v[16:19]
	v_mfma_f32_16x16x32_bf16 v[32:35], v[158:161], v[134:137], v[32:35]
	v_mfma_f32_16x16x32_bf16 v[48:51], v[162:165], v[134:137], v[48:51]
	v_mfma_f32_16x16x32_bf16 v[4:7], v[150:153], v[138:141], v[4:7]
	v_mfma_f32_16x16x32_bf16 v[20:23], v[154:157], v[138:141], v[20:23]
	v_mfma_f32_16x16x32_bf16 v[36:39], v[158:161], v[138:141], v[36:39]
	v_mfma_f32_16x16x32_bf16 v[52:55], v[162:165], v[138:141], v[52:55]
	v_mfma_f32_16x16x32_bf16 v[8:11], v[150:153], v[142:145], v[8:11]
	v_mfma_f32_16x16x32_bf16 v[24:27], v[154:157], v[142:145], v[24:27]
	v_mfma_f32_16x16x32_bf16 v[40:43], v[158:161], v[142:145], v[40:43]
	v_mfma_f32_16x16x32_bf16 v[56:59], v[162:165], v[142:145], v[56:59]
	v_mfma_f32_16x16x32_bf16 v[12:15], v[150:153], v[146:149], v[12:15]
	v_mfma_f32_16x16x32_bf16 v[28:31], v[154:157], v[146:149], v[28:31]
	v_mfma_f32_16x16x32_bf16 v[44:47], v[158:161], v[146:149], v[44:47]
	v_mfma_f32_16x16x32_bf16 v[60:63], v[162:165], v[146:149], v[60:63]
	v_mul_f32_e32 v170, v98, v242
	v_mul_f32_e32 v171, v99, v243
	v_mul_f32_e32 v172, v100, v244
	v_mul_f32_e32 v173, v101, v245
	v_cvt_pk_bf16_f32 v174, v170, v171
	v_cvt_pk_bf16_f32 v175, v172, v173
	ds_write_b64 v188, v[174:175] offset:5120
	s_waitcnt vmcnt(6)
	s_add_i32 m0, s55, 0
	s_nop 0
	global_load_lds_dwordx4 v232, s[42:43]
	s_add_i32 m0, s55, 1024
	s_nop 0
	global_load_lds_dwordx4 v233, s[42:43]
	s_add_i32 m0, s55, 2048
	s_nop 0
	global_load_lds_dwordx4 v234, s[42:43]
	s_add_i32 m0, s55, 3072
	s_nop 0
	global_load_lds_dwordx4 v235, s[42:43]
	ds_read_b64_tr_b16 v[150:151], v183 offset:4096
	ds_read_b64_tr_b16 v[152:153], v183 offset:4608
	ds_read_b64_tr_b16 v[154:155], v184 offset:4096
	ds_read_b64_tr_b16 v[156:157], v184 offset:4608
	ds_read_b64_tr_b16 v[158:159], v185 offset:4096
	ds_read_b64_tr_b16 v[160:161], v185 offset:4608
	ds_read_b64_tr_b16 v[162:163], v186 offset:4096
	ds_read_b64_tr_b16 v[164:165], v186 offset:4608
	s_add_i32 s41, s27, 1
	v_readlane_b32 s37, v236, s41
	s_cmp_lt_u32 s37, 32
	s_cbranch_scc0 .Lret_wctx_57
	s_lshl_b32 s100, s37, 6
	s_cmp_eq_u32 s37, s9
	s_cbranch_scc1 .Lret_wdiag_58
	s_cmp_lt_u32 s37, s9
	s_cselect_b32 s101, s11, s12
	v_subrev_u32_e32 v170, s100, v203
	v_subrev_u32_e32 v171, s100, v204
	v_subrev_u32_e32 v172, s100, v205
	v_subrev_u32_e32 v173, s100, v206
	v_cvt_f32_i32_e32 v174, v170
	v_cvt_f32_i32_e32 v175, v171
	v_cvt_f32_i32_e32 v176, v172
	v_cvt_f32_i32_e32 v177, v173
	v_mul_f32_e64 v178, s101, |v174|
	v_mul_f32_e64 v179, s101, |v175|
	v_mul_f32_e64 v180, s101, |v176|
	v_mul_f32_e64 v181, s101, |v177|
	v_exp_f32_e32 v166, v178
	v_exp_f32_e32 v167, v179
	v_exp_f32_e32 v168, v180
	v_exp_f32_e32 v169, v181
	s_branch .Lret_wdone_59
